# fused differential attention: one pass per branch accumulates all 128 value columns (QK^T and softmax computed once instead of twice), hand-written body replaces the 4-pass diff loop
# speedup vs baseline: 1.0382x; 1.0382x over previous
;   #define DMA_K(t,slot) glds16(ksrc+(long)(t)*KVBLK*KP,(unsigned)__builtin_amdgcn_readfirstlane(kdst+(slot)))
;   #define DMA_V(t,slot) glds16(vsrc+(long)(t)*KVBLK*VP,(unsigned)__builtin_amdgcn_readfirstlane(vdst+(slot)))
;   int tidv; asm volatile("v_mbcnt_lo_u32_b32 %0, -1, 0\n\tv_mbcnt_hi_u32_b32 %0, -1, %0":"=v"(tidv)); tidv+=wave_*64;
;   const int tid=tidv,lane=tid&63,r32=lane&31,hi=lane>>5; const int wid=__builtin_amdgcn_readfirstlane(tid>>6);
;   const int q0=qb*QB;
;   const bf16*Qw=Qb+(long)(wid*QBLK)*QP;
;   const unsigned lds0=(unsigned)(uintptr_t)shm;
;   float*wsf=(float*)(shm+LDS_WS)+wid*64;
;   const bf16*ksrc=Kh+(long)lane*KP+wid*8;
;   const bf16*vsrc=Vh+(long)(16*(wid&3)+(lane>>2))*VP+(wid>>2)*32+(lane&3)*8;
;   const unsigned kdst=lds0+LDS_K+wid*1024, vdst=lds0+LDS_V+wid*1024;
;     ...
;   const int vb0=(int)(lds0+LDS_V)+((lane>>4)&1)*32+(lane&3)*8+(4*hi+((lane&15)>>2))*64;
;   const char*Kbase=shm+LDS_K; bf16x8 kf[8];
;   const lds_cptr shm3=(lds_cptr)shm; const lds_cptr kp0=shm3+LDS_K+hi*1024+r32*16; const lds_cptr vp0=shm3+LDS_V+((lane>>4)&1)*32+(lane&3)*8+(4*hi+((lane&15)>>2))*64;
;   const int NT=(q0+QB)/KVBLK;
;   const __attribute__((address_space(3))) unsigned* mimg=(const __attribute__((address_space(3))) unsigned*)(shm3+LDS_OST+wid*MWAVE)+r32;
;   DMA_K(0,0);DMA_V(0,0);DMA_K(1,SLOTB);
;   if constexpr(MASKED){
;     __attribute__((address_space(3))) u32x4* mdst=(__attribute__((address_space(3))) u32x4*)(shm3+LDS_OST+wid*MWAVE)+lane;
;     for(int i=0;i<=qb;++i){ const u32x4 v=((const u32x4*)mwave)[i*64+lane]; mdst[i*64]=v; }
;   }
;   bf16x8 qr[4];
;   #pragma unroll
;   for(int d0=0;d0<4;++d0)qr[d0]=*reinterpret_cast<const bf16x8*>(&Qw[(long)r32*QP+d0*16+hi*8]);
;   float mhat=0.f,l_reg=0.f;f32x16 o[2];o[0]=f32x16{};o[1]=f32x16{};f32x16 negm=f32x16{};asm volatile("":"+v"(negm));
;   const int qrel=wid*QBLK+r32;
; __device__ __forceinline__ void run(Frame& F, int qword) {
;     ...
;             for (int sp = 0; sp < 4; ++sp) {
;                 const int c = sp >> 1, vh = sp & 1;
;                 attn_body::attn_unit<8, false>(qb, QB + rq * 512 + (h * 2 + c) * 64, 512, KB + r0 * 512 + (h * 2 + c) * 64, 512, VB + r0 * 512 + h * 128 + vh * 64, 512,
;                                                ATT + rq * 1024 + 512 + h * 128, 1024, nullptr, shm, F.wave, sp < 2 ? 1 : (sp == 2 ? 2 : 3), vh, lam);
.Lfd_entry:
	v_readlane_b32 s8, v254, 11
	v_mbcnt_lo_u32_b32 v0, -1, 0
	v_mbcnt_hi_u32_b32 v0, -1, v0
	v_and_b32_e32 v2, 31, v0
	v_lshrrev_b32_e32 v3, 5, v0
	s_lshl_b32 s89, s79, 2
	s_add_i32 s89, s89, 4
	s_lshl_b32 s0, s8, 4
	v_lshlrev_b32_e32 v10, 10, v0
	v_add_u32_e32 v10, s0, v10
	s_and_b32 s0, s8, 3
	s_lshl_b32 s0, s0, 14
	s_lshr_b32 s1, s8, 2
	s_lshl_b32 s1, s1, 6
	s_add_i32 s0, s0, s1
	v_lshrrev_b32_e32 v4, 2, v0
	v_lshlrev_b32_e32 v4, 10, v4
	v_and_b32_e32 v5, 3, v0
	v_lshlrev_b32_e32 v5, 4, v5
	v_add3_u32 v11, v4, v5, s0
	v_add_u32_e32 v12, 0x80, v11
	v_lshlrev_b32_e32 v13, 10, v3
	v_lshl_add_u32 v13, v2, 4, v13
	v_bfe_u32 v4, v0, 4, 1
	v_lshlrev_b32_e32 v4, 5, v4
	v_and_b32_e32 v5, 3, v0
	v_lshl_add_u32 v4, v5, 3, v4
	v_bfe_u32 v5, v0, 2, 2
	v_lshl_add_u32 v5, v3, 2, v5
	v_lshl_add_u32 v15, v5, 6, v4
	v_add_u32_e32 v15, 0x6000, v15
	s_lshl_b32 s0, s8, 8
	s_add_i32 s0, s0, 0x12000
	v_lshl_add_u32 v44, v2, 2, s0
	v_lshl_add_u32 v45, v3, 4, s0
	s_lshl_b32 s0, s8, 13
	v_lshl_add_u32 v46, v3, 10, s0
	v_lshl_add_u32 v46, v2, 1, v46
	v_lshl_add_u32 v219, v0, 4, s0
	v_lshrrev_b32_e32 v4, 4, v0
	v_and_b32_e32 v5, 15, v0
	v_lshlrev_b32_e32 v5, 4, v5
	v_lshl_add_u32 v252, v4, 11, v5
	v_lshlrev_b32_e32 v39, 10, v2
	v_lshl_add_u32 v39, v3, 4, v39
	s_lshl_b32 s0, s8, 5
	s_add_i32 s0, s0, s78
	v_add_u32_e32 v33, s0, v2
	v_lshlrev_b32_e32 v4, 2, v3
	v_sub_u32_e32 v33, v33, v4
	s_lshl_b32 s0, s8, 5
	s_add_i32 s0, s0, s26
	s_lshl_b32 s1, s28, 8
	s_add_i32 s1, s1, 0x400
	s_mov_b32 s3, 0
	s_mov_b32 s2, s0
	s_lshl_b64 s[2:3], s[2:3], 11
	s_add_u32 s2, s2, s1
	s_addc_u32 s3, s3, 0
	s_add_u32 s86, s66, s2
	s_addc_u32 s87, s67, s3
	s_mov_b32 s90, 0
.Lfd_pass:
	s_lshl_b32 s0, s28, 1
	s_add_i32 s0, s0, s90
	s_lshl_b32 s0, s0, 7
	s_mov_b32 s3, 0
	s_mov_b32 s2, s30
	s_lshl_b64 s[2:3], s[2:3], 21
	s_add_u32 s80, s62, s2
	s_addc_u32 s81, s63, s3
	s_add_u32 s80, s80, s0
	s_addc_u32 s81, s81, 0
	s_lshl_b32 s1, s28, 8
	s_add_u32 s82, s64, s2
	s_addc_u32 s83, s65, s3
	s_add_u32 s82, s82, s1
	s_addc_u32 s83, s83, 0
	s_lshl_b32 s1, s8, 5
	s_add_i32 s1, s1, s26
	s_mov_b32 s3, 0
	s_mov_b32 s2, s1
	s_lshl_b64 s[2:3], s[2:3], 10
	s_add_u32 s84, s60, s2
	s_addc_u32 s85, s61, s3
	s_add_u32 s84, s84, s0
	s_addc_u32 s85, s85, 0
	global_load_dwordx4 v[160:163], v39, s[84:85] offset:0
	global_load_dwordx4 v[164:167], v39, s[84:85] offset:32
	global_load_dwordx4 v[168:171], v39, s[84:85] offset:64
	global_load_dwordx4 v[172:175], v39, s[84:85] offset:96
	v_mov_b32_e32 v48, 0
	v_mov_b32_e32 v49, 0
	v_mov_b32_e32 v50, 0
	v_mov_b32_e32 v51, 0
	v_mov_b32_e32 v52, 0
	v_mov_b32_e32 v53, 0
	v_mov_b32_e32 v54, 0
	v_mov_b32_e32 v55, 0
	v_mov_b32_e32 v56, 0
	v_mov_b32_e32 v57, 0
	v_mov_b32_e32 v58, 0
	v_mov_b32_e32 v59, 0
	v_mov_b32_e32 v60, 0
	v_mov_b32_e32 v61, 0
	v_mov_b32_e32 v62, 0
	v_mov_b32_e32 v63, 0
	v_mov_b32_e32 v64, 0
	v_mov_b32_e32 v65, 0
	v_mov_b32_e32 v66, 0
	v_mov_b32_e32 v67, 0
	v_mov_b32_e32 v68, 0
	v_mov_b32_e32 v69, 0
	v_mov_b32_e32 v70, 0
	v_mov_b32_e32 v71, 0
	v_mov_b32_e32 v72, 0
	v_mov_b32_e32 v73, 0
	v_mov_b32_e32 v74, 0
	v_mov_b32_e32 v75, 0
	v_mov_b32_e32 v76, 0
	v_mov_b32_e32 v77, 0
	v_mov_b32_e32 v78, 0
	v_mov_b32_e32 v79, 0
	v_mov_b32_e32 v80, 0
	v_mov_b32_e32 v81, 0
	v_mov_b32_e32 v82, 0
	v_mov_b32_e32 v83, 0
	v_mov_b32_e32 v84, 0
	v_mov_b32_e32 v85, 0
	v_mov_b32_e32 v86, 0
	v_mov_b32_e32 v87, 0
	v_mov_b32_e32 v88, 0
	v_mov_b32_e32 v89, 0
	v_mov_b32_e32 v90, 0
	v_mov_b32_e32 v91, 0
	v_mov_b32_e32 v92, 0
	v_mov_b32_e32 v93, 0
	v_mov_b32_e32 v94, 0
	v_mov_b32_e32 v95, 0
	v_mov_b32_e32 v96, 0
	v_mov_b32_e32 v97, 0
	v_mov_b32_e32 v98, 0
	v_mov_b32_e32 v99, 0
	v_mov_b32_e32 v100, 0
	v_mov_b32_e32 v101, 0
	v_mov_b32_e32 v102, 0
	v_mov_b32_e32 v103, 0
	v_mov_b32_e32 v104, 0
	v_mov_b32_e32 v105, 0
	v_mov_b32_e32 v106, 0
	v_mov_b32_e32 v107, 0
	v_mov_b32_e32 v108, 0
	v_mov_b32_e32 v109, 0
	v_mov_b32_e32 v110, 0
	v_mov_b32_e32 v111, 0
	v_mov_b32_e32 v144, 0
	v_mov_b32_e32 v145, 0
	v_mov_b32_e32 v146, 0
	v_mov_b32_e32 v147, 0
	v_mov_b32_e32 v148, 0
	v_mov_b32_e32 v149, 0
	v_mov_b32_e32 v150, 0
	v_mov_b32_e32 v151, 0
	v_mov_b32_e32 v152, 0
	v_mov_b32_e32 v153, 0
	v_mov_b32_e32 v154, 0
	v_mov_b32_e32 v155, 0
	v_mov_b32_e32 v156, 0
	v_mov_b32_e32 v157, 0
	v_mov_b32_e32 v158, 0
	v_mov_b32_e32 v159, 0
	v_mov_b32_e32 v34, 0
	v_mov_b32_e32 v35, 0
	s_mov_b32 s91, 0
	s_mov_b32 s92, 0x2000
	s_mov_b32 s93, 0x4000
	s_lshl_b32 s29, s8, 10
	s_mov_b64 s[44:45], s[80:81]
	s_mov_b64 s[46:47], s[82:83]
	s_add_i32 s1, s91, s29
	s_mov_b32 m0, s1
	s_lshl_b32 s2, s91, 1
	global_load_lds_dwordx4 v10, s[44:45]
	s_add_i32 s2, s2, s29
	s_add_i32 s2, s2, 0x6000
	s_mov_b32 m0, s2
	s_add_i32 s2, s2, 0x2000
	global_load_lds_dwordx4 v11, s[46:47]
	s_mov_b32 m0, s2
	s_nop 0
	global_load_lds_dwordx4 v12, s[46:47]
	s_mov_b32 s94, 1
	s_lshl_b32 s0, s94, 16
	s_add_u32 s44, s80, s0
	s_addc_u32 s45, s81, 0
	s_add_u32 s46, s82, s0
	s_addc_u32 s47, s83, 0
	s_add_i32 s1, s92, s29
	s_mov_b32 m0, s1
	s_lshl_b32 s2, s92, 1
	global_load_lds_dwordx4 v10, s[44:45]
	s_add_i32 s2, s2, s29
	s_add_i32 s2, s2, 0x6000
	s_mov_b32 m0, s2
	s_add_i32 s2, s2, 0x2000
	global_load_lds_dwordx4 v11, s[46:47]
	s_mov_b32 m0, s2
	s_nop 0
	global_load_lds_dwordx4 v12, s[46:47]
	s_mov_b32 s88, 0
; __device__ __forceinline__ void cmask(f32x16&p0,f32x16&p1,int jb,int qrel,int hi,int wrow){
;   const float NEG=-INFINITY; int kb=64*jb+4*hi;
;   if(64*jb+63<=wrow) return;
;   if(64*jb>wrow+31){
;     #pragma unroll
;     for(int r=0;r<16;++r){p0[r]=NEG;p1[r]=NEG;}
;     return; }
;   #pragma unroll
;   for(int r=0;r<16;++r){int kv=kb+(r&3)+8*(r>>2); if(kv>qrel)p0[r]=NEG; if(kv+32>qrel)p1[r]=NEG;}
; }
.Lfd_loop:
	s_waitcnt vmcnt(3)
	s_barrier
	s_add_i32 s94, s88, 2
	s_add_i32 s0, s89, -1
	s_min_i32 s94, s94, s0
	s_lshl_b32 s0, s94, 16
	s_add_u32 s44, s80, s0
	s_addc_u32 s45, s81, 0
	s_add_u32 s46, s82, s0
	s_addc_u32 s47, s83, 0
	s_add_i32 s1, s93, s29
	s_mov_b32 m0, s1
	s_lshl_b32 s2, s93, 1
	global_load_lds_dwordx4 v10, s[44:45]
	s_add_i32 s2, s2, s29
	s_add_i32 s2, s2, 0x6000
	s_mov_b32 m0, s2
	s_add_i32 s2, s2, 0x2000
	global_load_lds_dwordx4 v11, s[46:47]
	s_mov_b32 m0, s2
	s_nop 0
	global_load_lds_dwordx4 v12, s[46:47]
	v_add_u32_e32 v14, s91, v13
	ds_read_b128 v[176:179], v14 offset:0
	ds_read_b128 v[180:183], v14 offset:512
	ds_read_b128 v[184:187], v14 offset:2048
	ds_read_b128 v[188:191], v14 offset:2560
	ds_read_b128 v[192:195], v14 offset:4096
	ds_read_b128 v[196:199], v14 offset:4608
	ds_read_b128 v[200:203], v14 offset:6144
	ds_read_b128 v[204:207], v14 offset:6656
	s_lshl_b32 s0, s91, 1
	v_add_u32_e32 v32, s0, v15
	s_waitcnt lgkmcnt(0)
	v_mfma_f32_32x32x16_bf16 v[112:127], v[176:179], v[160:163], v[144:159]
	v_mfma_f32_32x32x16_bf16 v[128:143], v[180:183], v[160:163], v[144:159]
	v_mfma_f32_32x32x16_bf16 v[112:127], v[184:187], v[164:167], v[112:127]
	v_mfma_f32_32x32x16_bf16 v[128:143], v[188:191], v[164:167], v[128:143]
	v_mfma_f32_32x32x16_bf16 v[112:127], v[192:195], v[168:171], v[112:127]
	v_mfma_f32_32x32x16_bf16 v[128:143], v[196:199], v[168:171], v[128:143]
	v_mfma_f32_32x32x16_bf16 v[112:127], v[200:203], v[172:175], v[112:127]
	v_mfma_f32_32x32x16_bf16 v[128:143], v[204:207], v[172:175], v[128:143]
	ds_read_b64_tr_b16 v[220:221], v32 offset:8192
	ds_read_b64_tr_b16 v[222:223], v32 offset:8704
	ds_read_b64_tr_b16 v[224:225], v32 offset:9216
	ds_read_b64_tr_b16 v[226:227], v32 offset:9728
	ds_read_b64_tr_b16 v[228:229], v32 offset:10240
	ds_read_b64_tr_b16 v[230:231], v32 offset:10752
	ds_read_b64_tr_b16 v[232:233], v32 offset:11264
	ds_read_b64_tr_b16 v[234:235], v32 offset:11776
	ds_read_b64_tr_b16 v[236:237], v32 offset:12288
	ds_read_b64_tr_b16 v[238:239], v32 offset:12800
	ds_read_b64_tr_b16 v[240:241], v32 offset:13312
	ds_read_b64_tr_b16 v[242:243], v32 offset:13824
	ds_read_b64_tr_b16 v[244:245], v32 offset:14336
	ds_read_b64_tr_b16 v[246:247], v32 offset:14848
	ds_read_b64_tr_b16 v[248:249], v32 offset:15360
	ds_read_b64_tr_b16 v[250:251], v32 offset:15872
	ds_read_b64_tr_b16 v[176:177], v32 offset:0
	ds_read_b64_tr_b16 v[178:179], v32 offset:512
	ds_read_b64_tr_b16 v[180:181], v32 offset:1024
	ds_read_b64_tr_b16 v[182:183], v32 offset:1536
	ds_read_b64_tr_b16 v[184:185], v32 offset:2048
	ds_read_b64_tr_b16 v[186:187], v32 offset:2560
	ds_read_b64_tr_b16 v[188:189], v32 offset:3072
	ds_read_b64_tr_b16 v[190:191], v32 offset:3584
	ds_read_b64_tr_b16 v[192:193], v32 offset:4096
	ds_read_b64_tr_b16 v[194:195], v32 offset:4608
	ds_read_b64_tr_b16 v[196:197], v32 offset:5120
	ds_read_b64_tr_b16 v[198:199], v32 offset:5632
	ds_read_b64_tr_b16 v[200:201], v32 offset:6144
	ds_read_b64_tr_b16 v[202:203], v32 offset:6656
	ds_read_b64_tr_b16 v[204:205], v32 offset:7168
	ds_read_b64_tr_b16 v[206:207], v32 offset:7680
	s_add_i32 s0, s89, -4
	s_cmp_lt_i32 s88, s0
	s_cbranch_scc1 .Lfd_nomask
	s_lshl_b32 s0, s88, 6
	v_subrev_u32_e32 v4, s0, v33
	v_cmp_gt_i32_e64 s[36:37], 0, v4
	v_cmp_gt_i32_e64 s[38:39], 1, v4
	v_cmp_gt_i32_e64 s[48:49], 2, v4
	v_cmp_gt_i32_e64 s[50:51], 3, v4
	v_cndmask_b32_e64 v112, v112, v47, s[36:37]
	v_cndmask_b32_e64 v113, v113, v47, s[38:39]
	v_cndmask_b32_e64 v114, v114, v47, s[48:49]
	v_cndmask_b32_e64 v115, v115, v47, s[50:51]
	v_cmp_gt_i32_e64 s[36:37], 8, v4
	v_cmp_gt_i32_e64 s[38:39], 9, v4
	v_cmp_gt_i32_e64 s[48:49], 10, v4
	v_cmp_gt_i32_e64 s[50:51], 11, v4
	v_cndmask_b32_e64 v116, v116, v47, s[36:37]
	v_cndmask_b32_e64 v117, v117, v47, s[38:39]
	v_cndmask_b32_e64 v118, v118, v47, s[48:49]
	v_cndmask_b32_e64 v119, v119, v47, s[50:51]
	v_cmp_gt_i32_e64 s[36:37], 16, v4
	v_cmp_gt_i32_e64 s[38:39], 17, v4
	v_cmp_gt_i32_e64 s[48:49], 18, v4
	v_cmp_gt_i32_e64 s[50:51], 19, v4
	v_cndmask_b32_e64 v120, v120, v47, s[36:37]
	v_cndmask_b32_e64 v121, v121, v47, s[38:39]
	v_cndmask_b32_e64 v122, v122, v47, s[48:49]
	v_cndmask_b32_e64 v123, v123, v47, s[50:51]
	v_cmp_gt_i32_e64 s[36:37], 24, v4
	v_cmp_gt_i32_e64 s[38:39], 25, v4
	v_cmp_gt_i32_e64 s[48:49], 26, v4
	v_cmp_gt_i32_e64 s[50:51], 27, v4
	v_cndmask_b32_e64 v124, v124, v47, s[36:37]
	v_cndmask_b32_e64 v125, v125, v47, s[38:39]
	v_cndmask_b32_e64 v126, v126, v47, s[48:49]
	v_cndmask_b32_e64 v127, v127, v47, s[50:51]
	v_cmp_gt_i32_e64 s[36:37], 32, v4
	v_cmp_gt_i32_e64 s[38:39], 33, v4
	v_cmp_gt_i32_e64 s[48:49], 34, v4
	v_cmp_gt_i32_e64 s[50:51], 35, v4
	v_cndmask_b32_e64 v128, v128, v47, s[36:37]
	v_cndmask_b32_e64 v129, v129, v47, s[38:39]
	v_cndmask_b32_e64 v130, v130, v47, s[48:49]
	v_cndmask_b32_e64 v131, v131, v47, s[50:51]
	v_cmp_gt_i32_e64 s[36:37], 40, v4
	v_cmp_gt_i32_e64 s[38:39], 41, v4
	v_cmp_gt_i32_e64 s[48:49], 42, v4
	v_cmp_gt_i32_e64 s[50:51], 43, v4
	v_cndmask_b32_e64 v132, v132, v47, s[36:37]
	v_cndmask_b32_e64 v133, v133, v47, s[38:39]
	v_cndmask_b32_e64 v134, v134, v47, s[48:49]
	v_cndmask_b32_e64 v135, v135, v47, s[50:51]
	v_cmp_gt_i32_e64 s[36:37], 48, v4
	v_cmp_gt_i32_e64 s[38:39], 49, v4
	v_cmp_gt_i32_e64 s[48:49], 50, v4
	v_cmp_gt_i32_e64 s[50:51], 51, v4
	v_cndmask_b32_e64 v136, v136, v47, s[36:37]
	v_cndmask_b32_e64 v137, v137, v47, s[38:39]
	v_cndmask_b32_e64 v138, v138, v47, s[48:49]
	v_cndmask_b32_e64 v139, v139, v47, s[50:51]
	v_cmp_gt_i32_e64 s[36:37], 56, v4
	v_cmp_gt_i32_e64 s[38:39], 57, v4
	v_cmp_gt_i32_e64 s[48:49], 58, v4
	v_cmp_gt_i32_e64 s[50:51], 59, v4
	v_cndmask_b32_e64 v140, v140, v47, s[36:37]
	v_cndmask_b32_e64 v141, v141, v47, s[38:39]
	v_cndmask_b32_e64 v142, v142, v47, s[48:49]
	v_cndmask_b32_e64 v143, v143, v47, s[50:51]
.Lfd_nomask:
	v_max3_f32 v36, v112, v113, v114
	v_max3_f32 v37, v128, v129, v130
	v_max3_f32 v36, v36, v115, v116
	v_max3_f32 v37, v37, v117, v118
	v_max3_f32 v36, v36, v119, v120
	v_max3_f32 v37, v37, v121, v122
	v_max3_f32 v36, v36, v123, v124
	v_max3_f32 v37, v37, v125, v126
	v_max3_f32 v36, v36, v127, v131
	v_max3_f32 v37, v37, v132, v133
	v_max3_f32 v36, v36, v134, v135
	v_max3_f32 v37, v37, v136, v137
	v_max3_f32 v36, v36, v138, v139
	v_max3_f32 v37, v37, v140, v141
	v_max3_f32 v36, v36, v142, v143
	v_max_f32_e32 v36, v36, v37
	v_mov_b32_e32 v37, v36
	s_nop 1
	v_permlane32_swap_b32_e32 v36, v37
	v_max_f32_e32 v36, v36, v37
	s_nop 0
	v_cmp_lt_f32_e32 vcc, s76, v36
	s_cbranch_vccz .Lfd_noresc
	v_max_f32_e32 v37, 0, v36
	v_add_f32_e32 v35, v35, v37
	v_sub_f32_e32 v112, v112, v37
	v_sub_f32_e32 v128, v128, v37
	v_sub_f32_e32 v113, v113, v37
	v_sub_f32_e32 v129, v129, v37
	v_sub_f32_e32 v114, v114, v37
	v_sub_f32_e32 v130, v130, v37
	v_sub_f32_e32 v115, v115, v37
	v_sub_f32_e32 v131, v131, v37
	v_sub_f32_e32 v116, v116, v37
	v_sub_f32_e32 v132, v132, v37
	v_sub_f32_e32 v117, v117, v37
	v_sub_f32_e32 v133, v133, v37
	v_sub_f32_e32 v118, v118, v37
	v_sub_f32_e32 v134, v134, v37
	v_sub_f32_e32 v119, v119, v37
	v_sub_f32_e32 v135, v135, v37
	v_sub_f32_e32 v120, v120, v37
	v_sub_f32_e32 v136, v136, v37
	v_sub_f32_e32 v121, v121, v37
	v_sub_f32_e32 v137, v137, v37
	v_sub_f32_e32 v122, v122, v37
	v_sub_f32_e32 v138, v138, v37
	v_sub_f32_e32 v123, v123, v37
	v_sub_f32_e32 v139, v139, v37
	v_sub_f32_e32 v124, v124, v37
	v_sub_f32_e32 v140, v140, v37
	v_sub_f32_e32 v125, v125, v37
	v_sub_f32_e32 v141, v141, v37
	v_sub_f32_e32 v126, v126, v37
	v_sub_f32_e32 v142, v142, v37
	v_sub_f32_e32 v127, v127, v37
	v_sub_f32_e32 v143, v143, v37
	v_sub_f32_e32 v144, 0, v35
	v_sub_f32_e32 v145, 0, v35
	v_sub_f32_e32 v146, 0, v35
	v_sub_f32_e32 v147, 0, v35
	v_sub_f32_e32 v148, 0, v35
	v_sub_f32_e32 v149, 0, v35
	v_sub_f32_e32 v150, 0, v35
	v_sub_f32_e32 v151, 0, v35
	v_sub_f32_e32 v152, 0, v35
	v_sub_f32_e32 v153, 0, v35
	v_sub_f32_e32 v154, 0, v35
	v_sub_f32_e32 v155, 0, v35
	v_sub_f32_e32 v156, 0, v35
	v_sub_f32_e32 v157, 0, v35
	v_sub_f32_e32 v158, 0, v35
	v_sub_f32_e32 v159, 0, v35
	v_sub_f32_e32 v38, 0, v37
	v_exp_f32_e32 v38, v38
	s_nop 0
	v_mul_f32_e32 v34, v34, v38
	s_waitcnt lgkmcnt(0)
	ds_write_b32 v44, v38
	s_waitcnt lgkmcnt(0)
	ds_read_b128 v[208:211], v45 offset:0
	ds_read_b128 v[212:215], v45 offset:32
	ds_read_b128 v[40:43], v45 offset:64
	ds_read_b128 v[6:9], v45 offset:96
	s_waitcnt lgkmcnt(0)
	v_mul_f32_e32 v48, v48, v208
	v_mul_f32_e32 v49, v49, v209
	v_mul_f32_e32 v50, v50, v210
	v_mul_f32_e32 v51, v51, v211
	v_mul_f32_e32 v52, v52, v212
	v_mul_f32_e32 v53, v53, v213
	v_mul_f32_e32 v54, v54, v214
	v_mul_f32_e32 v55, v55, v215
	v_mul_f32_e32 v56, v56, v40
	v_mul_f32_e32 v57, v57, v41
	v_mul_f32_e32 v58, v58, v42
	v_mul_f32_e32 v59, v59, v43
	v_mul_f32_e32 v60, v60, v6
	v_mul_f32_e32 v61, v61, v7
	v_mul_f32_e32 v62, v62, v8
	v_mul_f32_e32 v63, v63, v9
	v_mul_f32_e32 v64, v64, v208
	v_mul_f32_e32 v65, v65, v209
	v_mul_f32_e32 v66, v66, v210
	v_mul_f32_e32 v67, v67, v211
	v_mul_f32_e32 v68, v68, v212
	v_mul_f32_e32 v69, v69, v213
	v_mul_f32_e32 v70, v70, v214
	v_mul_f32_e32 v71, v71, v215
	v_mul_f32_e32 v72, v72, v40
	v_mul_f32_e32 v73, v73, v41
	v_mul_f32_e32 v74, v74, v42
	v_mul_f32_e32 v75, v75, v43
	v_mul_f32_e32 v76, v76, v6
	v_mul_f32_e32 v77, v77, v7
	v_mul_f32_e32 v78, v78, v8
	v_mul_f32_e32 v79, v79, v9
	v_mul_f32_e32 v80, v80, v208
	v_mul_f32_e32 v81, v81, v209
	v_mul_f32_e32 v82, v82, v210
	v_mul_f32_e32 v83, v83, v211
	v_mul_f32_e32 v84, v84, v212
	v_mul_f32_e32 v85, v85, v213
	v_mul_f32_e32 v86, v86, v214
	v_mul_f32_e32 v87, v87, v215
	v_mul_f32_e32 v88, v88, v40
	v_mul_f32_e32 v89, v89, v41
	v_mul_f32_e32 v90, v90, v42
	v_mul_f32_e32 v91, v91, v43
	v_mul_f32_e32 v92, v92, v6
	v_mul_f32_e32 v93, v93, v7
	v_mul_f32_e32 v94, v94, v8
	v_mul_f32_e32 v95, v95, v9
	v_mul_f32_e32 v96, v96, v208
	v_mul_f32_e32 v97, v97, v209
	v_mul_f32_e32 v98, v98, v210
	v_mul_f32_e32 v99, v99, v211
	v_mul_f32_e32 v100, v100, v212
	v_mul_f32_e32 v101, v101, v213
	v_mul_f32_e32 v102, v102, v214
	v_mul_f32_e32 v103, v103, v215
	v_mul_f32_e32 v104, v104, v40
	v_mul_f32_e32 v105, v105, v41
	v_mul_f32_e32 v106, v106, v42
	v_mul_f32_e32 v107, v107, v43
	v_mul_f32_e32 v108, v108, v6
	v_mul_f32_e32 v109, v109, v7
	v_mul_f32_e32 v110, v110, v8
	v_mul_f32_e32 v111, v111, v9
; __device__ __forceinline__ int crow(int r,int hi){return (r&3)+8*(r>>2)+4*hi;}
;     ...
;   {auto rr=__builtin_amdgcn_permlane32_swap(__float_as_uint(l_reg),__float_as_uint(l_reg),false,false);l_reg=__uint_as_float(rr[0])+__uint_as_float(rr[1]);}
;   if(hi==0)wsf[32+r32]=l_reg;asm volatile("s_waitcnt lgkmcnt(0)":::"memory");
;   float rli[16];
;   #pragma unroll
;   for(int r=0;r<16;++r)rli[r]=__builtin_amdgcn_rcpf(wsf[32+crow(r,hi)]);
.Lfd_noresc:
	v_exp_f32_e32 v112, v112
	v_exp_f32_e32 v113, v113
	v_exp_f32_e32 v114, v114
	v_exp_f32_e32 v115, v115
	v_exp_f32_e32 v116, v116
	v_exp_f32_e32 v117, v117
	v_exp_f32_e32 v118, v118
	v_exp_f32_e32 v119, v119
	v_exp_f32_e32 v120, v120
	v_exp_f32_e32 v121, v121
	v_exp_f32_e32 v122, v122
	v_exp_f32_e32 v123, v123
	v_exp_f32_e32 v124, v124
	v_exp_f32_e32 v125, v125
	v_exp_f32_e32 v126, v126
	v_exp_f32_e32 v127, v127
	v_exp_f32_e32 v128, v128
	v_exp_f32_e32 v129, v129
	v_exp_f32_e32 v130, v130
	v_exp_f32_e32 v131, v131
	v_exp_f32_e32 v132, v132
	v_exp_f32_e32 v133, v133
	v_exp_f32_e32 v134, v134
	v_exp_f32_e32 v135, v135
	v_exp_f32_e32 v136, v136
	v_exp_f32_e32 v137, v137
	v_exp_f32_e32 v138, v138
	v_exp_f32_e32 v139, v139
	v_exp_f32_e32 v140, v140
	v_exp_f32_e32 v141, v141
	v_exp_f32_e32 v142, v142
	v_exp_f32_e32 v143, v143
	s_nop 0
	v_add_f32_e32 v4, v112, v113
	v_add_f32_e32 v5, v128, v129
	v_add_f32_e32 v4, v114, v4
	v_add_f32_e32 v5, v130, v5
	v_add_f32_e32 v4, v115, v4
	v_add_f32_e32 v5, v131, v5
	v_add_f32_e32 v4, v116, v4
	v_add_f32_e32 v5, v132, v5
	v_add_f32_e32 v4, v117, v4
	v_add_f32_e32 v5, v133, v5
	v_add_f32_e32 v4, v118, v4
	v_add_f32_e32 v5, v134, v5
	v_add_f32_e32 v4, v119, v4
	v_add_f32_e32 v5, v135, v5
	v_add_f32_e32 v4, v120, v4
	v_add_f32_e32 v5, v136, v5
	v_add_f32_e32 v4, v121, v4
	v_add_f32_e32 v5, v137, v5
	v_add_f32_e32 v4, v122, v4
	v_add_f32_e32 v5, v138, v5
	v_add_f32_e32 v4, v123, v4
	v_add_f32_e32 v5, v139, v5
	v_add_f32_e32 v4, v124, v4
	v_add_f32_e32 v5, v140, v5
	v_add_f32_e32 v4, v125, v4
	v_add_f32_e32 v5, v141, v5
	v_add_f32_e32 v4, v126, v4
	v_add_f32_e32 v5, v142, v5
	v_add_f32_e32 v4, v127, v4
	v_add_f32_e32 v5, v143, v5
	v_add_f32_e32 v4, v4, v5
	v_add_f32_e32 v34, v34, v4
	v_cvt_pk_bf16_f32 v208, v112, v113
	v_cvt_pk_bf16_f32 v209, v114, v115
	v_cvt_pk_bf16_f32 v210, v116, v117
	v_cvt_pk_bf16_f32 v211, v118, v119
	v_cvt_pk_bf16_f32 v212, v120, v121
	v_cvt_pk_bf16_f32 v213, v122, v123
	v_cvt_pk_bf16_f32 v214, v124, v125
	v_cvt_pk_bf16_f32 v215, v126, v127
	v_cvt_pk_bf16_f32 v40, v128, v129
	v_cvt_pk_bf16_f32 v41, v130, v131
	v_cvt_pk_bf16_f32 v42, v132, v133
	v_cvt_pk_bf16_f32 v43, v134, v135
	v_cvt_pk_bf16_f32 v6, v136, v137
	v_cvt_pk_bf16_f32 v7, v138, v139
	v_cvt_pk_bf16_f32 v8, v140, v141
	v_cvt_pk_bf16_f32 v9, v142, v143
	s_waitcnt lgkmcnt(0)
	v_mfma_f32_32x32x16_bf16 v[48:63], v[208:211], v[176:179], v[48:63]
	v_mfma_f32_32x32x16_bf16 v[64:79], v[208:211], v[192:195], v[64:79]
	v_mfma_f32_32x32x16_bf16 v[80:95], v[208:211], v[220:223], v[80:95]
	v_mfma_f32_32x32x16_bf16 v[96:111], v[208:211], v[236:239], v[96:111]
	v_mfma_f32_32x32x16_bf16 v[48:63], v[212:215], v[180:183], v[48:63]
	v_mfma_f32_32x32x16_bf16 v[64:79], v[212:215], v[196:199], v[64:79]
	v_mfma_f32_32x32x16_bf16 v[80:95], v[212:215], v[224:227], v[80:95]
	v_mfma_f32_32x32x16_bf16 v[96:111], v[212:215], v[240:243], v[96:111]
	v_mfma_f32_32x32x16_bf16 v[48:63], v[40:43], v[184:187], v[48:63]
	v_mfma_f32_32x32x16_bf16 v[64:79], v[40:43], v[200:203], v[64:79]
	v_mfma_f32_32x32x16_bf16 v[80:95], v[40:43], v[228:231], v[80:95]
	v_mfma_f32_32x32x16_bf16 v[96:111], v[40:43], v[244:247], v[96:111]
	v_mfma_f32_32x32x16_bf16 v[48:63], v[6:9], v[188:191], v[48:63]
	v_mfma_f32_32x32x16_bf16 v[64:79], v[6:9], v[204:207], v[64:79]
	v_mfma_f32_32x32x16_bf16 v[80:95], v[6:9], v[232:235], v[80:95]
	v_mfma_f32_32x32x16_bf16 v[96:111], v[6:9], v[248:251], v[96:111]
	s_mov_b32 s0, s91
	s_mov_b32 s91, s92
	s_mov_b32 s92, s93
	s_mov_b32 s93, s0
	s_add_i32 s88, s88, 1
	s_cmp_lt_i32 s88, s89
	s_cbranch_scc1 .Lfd_loop
	s_waitcnt vmcnt(0)
	s_barrier
	s_nop 7
	s_nop 7
	v_mov_b32_e32 v4, v34
	v_mov_b32_e32 v5, v34
	s_nop 1
	v_permlane32_swap_b32_e32 v4, v5
	v_add_f32_e32 v4, v4, v5
	ds_write_b32 v44, v4 offset:128
	s_waitcnt lgkmcnt(0)
	ds_read_b128 v[112:115], v45 offset:128
	ds_read_b128 v[116:119], v45 offset:160
	ds_read_b128 v[120:123], v45 offset:192
	ds_read_b128 v[124:127], v45 offset:224
	s_waitcnt lgkmcnt(0)
	v_rcp_f32_e32 v112, v112
	v_rcp_f32_e32 v113, v113
	v_rcp_f32_e32 v114, v114
	v_rcp_f32_e32 v115, v115
	v_rcp_f32_e32 v116, v116
	v_rcp_f32_e32 v117, v117
	v_rcp_f32_e32 v118, v118
	v_rcp_f32_e32 v119, v119
	v_rcp_f32_e32 v120, v120
	v_rcp_f32_e32 v121, v121
	v_rcp_f32_e32 v122, v122
	v_rcp_f32_e32 v123, v123
	v_rcp_f32_e32 v124, v124
	v_rcp_f32_e32 v125, v125
	v_rcp_f32_e32 v126, v126
	v_rcp_f32_e32 v127, v127
	s_nop 0
	s_cmp_lg_u32 s90, 0
	s_cbranch_scc1 .Lfd_epi1
; __device__ __forceinline__ unsigned cvtpk_s(float lo,float hi){f32x2_t v={lo,hi};bf16x2_t b=__builtin_convertvector(v,bf16x2_t);return __builtin_bit_cast(unsigned,b);}
; #define ATTN_STORE16(p,v) st16_wt((p),(v))
;     ...
;       #pragma unroll
;       for(int r=0;r<16;++r){
;         #pragma unroll
;         for(int d0=0;d0<2;++d0)stl[cr0(r)*64+d0*32]=(bf16)(cvtpk_s(o[d0][r]*rli[r],0.f)&0xffffu);}
;     }
;     asm volatile("s_waitcnt lgkmcnt(0)":::"memory");
;     if(emode==0){
;       #pragma unroll
;       for(int i=0;i<4;++i){const int row=i*8+(lane>>3),ch=lane&7; const u32x4 v=*(const u32x4*)(stg+row*64+ch*8); ATTN_STORE16(Ow+(long)row*OP+ch*8,v);}
	v_mul_f32_e32 v4, v48, v112
	v_cvt_pk_bf16_f32 v4, v4, v4
	ds_write_b16 v46, v4 offset:0
	v_mul_f32_e32 v4, v49, v113
	v_cvt_pk_bf16_f32 v4, v4, v4
	ds_write_b16 v46, v4 offset:256
	v_mul_f32_e32 v4, v50, v114
	v_cvt_pk_bf16_f32 v4, v4, v4
	ds_write_b16 v46, v4 offset:512
	v_mul_f32_e32 v4, v51, v115
	v_cvt_pk_bf16_f32 v4, v4, v4
	ds_write_b16 v46, v4 offset:768
	v_mul_f32_e32 v4, v52, v116
	v_cvt_pk_bf16_f32 v4, v4, v4
	ds_write_b16 v46, v4 offset:2048
	v_mul_f32_e32 v4, v53, v117
	v_cvt_pk_bf16_f32 v4, v4, v4
	ds_write_b16 v46, v4 offset:2304
	v_mul_f32_e32 v4, v54, v118
	v_cvt_pk_bf16_f32 v4, v4, v4
	ds_write_b16 v46, v4 offset:2560
	v_mul_f32_e32 v4, v55, v119
	v_cvt_pk_bf16_f32 v4, v4, v4
	ds_write_b16 v46, v4 offset:2816
	v_mul_f32_e32 v4, v56, v120
	v_cvt_pk_bf16_f32 v4, v4, v4
	ds_write_b16 v46, v4 offset:4096
	v_mul_f32_e32 v4, v57, v121
	v_cvt_pk_bf16_f32 v4, v4, v4
	ds_write_b16 v46, v4 offset:4352
	v_mul_f32_e32 v4, v58, v122
	v_cvt_pk_bf16_f32 v4, v4, v4
	ds_write_b16 v46, v4 offset:4608
	v_mul_f32_e32 v4, v59, v123
	v_cvt_pk_bf16_f32 v4, v4, v4
	ds_write_b16 v46, v4 offset:4864
	v_mul_f32_e32 v4, v60, v124
	v_cvt_pk_bf16_f32 v4, v4, v4
	ds_write_b16 v46, v4 offset:6144
	v_mul_f32_e32 v4, v61, v125
	v_cvt_pk_bf16_f32 v4, v4, v4
	ds_write_b16 v46, v4 offset:6400
	v_mul_f32_e32 v4, v62, v126
	v_cvt_pk_bf16_f32 v4, v4, v4
	ds_write_b16 v46, v4 offset:6656
	v_mul_f32_e32 v4, v63, v127
	v_cvt_pk_bf16_f32 v4, v4, v4
	ds_write_b16 v46, v4 offset:6912
	v_mul_f32_e32 v4, v64, v112
	v_cvt_pk_bf16_f32 v4, v4, v4
	ds_write_b16 v46, v4 offset:64
	v_mul_f32_e32 v4, v65, v113
	v_cvt_pk_bf16_f32 v4, v4, v4
	ds_write_b16 v46, v4 offset:320
	v_mul_f32_e32 v4, v66, v114
	v_cvt_pk_bf16_f32 v4, v4, v4
	ds_write_b16 v46, v4 offset:576
	v_mul_f32_e32 v4, v67, v115
	v_cvt_pk_bf16_f32 v4, v4, v4
	ds_write_b16 v46, v4 offset:832
	v_mul_f32_e32 v4, v68, v116
	v_cvt_pk_bf16_f32 v4, v4, v4
	ds_write_b16 v46, v4 offset:2112
	v_mul_f32_e32 v4, v69, v117
	v_cvt_pk_bf16_f32 v4, v4, v4
	ds_write_b16 v46, v4 offset:2368
	v_mul_f32_e32 v4, v70, v118
	v_cvt_pk_bf16_f32 v4, v4, v4
	ds_write_b16 v46, v4 offset:2624
	v_mul_f32_e32 v4, v71, v119
	v_cvt_pk_bf16_f32 v4, v4, v4
	ds_write_b16 v46, v4 offset:2880
	v_mul_f32_e32 v4, v72, v120
	v_cvt_pk_bf16_f32 v4, v4, v4
	ds_write_b16 v46, v4 offset:4160
	v_mul_f32_e32 v4, v73, v121
	v_cvt_pk_bf16_f32 v4, v4, v4
	ds_write_b16 v46, v4 offset:4416
	v_mul_f32_e32 v4, v74, v122
	v_cvt_pk_bf16_f32 v4, v4, v4
	ds_write_b16 v46, v4 offset:4672
	v_mul_f32_e32 v4, v75, v123
	v_cvt_pk_bf16_f32 v4, v4, v4
	ds_write_b16 v46, v4 offset:4928
	v_mul_f32_e32 v4, v76, v124
	v_cvt_pk_bf16_f32 v4, v4, v4
	ds_write_b16 v46, v4 offset:6208
	v_mul_f32_e32 v4, v77, v125
	v_cvt_pk_bf16_f32 v4, v4, v4
	ds_write_b16 v46, v4 offset:6464
	v_mul_f32_e32 v4, v78, v126
	v_cvt_pk_bf16_f32 v4, v4, v4
	ds_write_b16 v46, v4 offset:6720
	v_mul_f32_e32 v4, v79, v127
	v_cvt_pk_bf16_f32 v4, v4, v4
	ds_write_b16 v46, v4 offset:6976
	v_mul_f32_e32 v4, v80, v112
	v_cvt_pk_bf16_f32 v4, v4, v4
	ds_write_b16 v46, v4 offset:128
	v_mul_f32_e32 v4, v81, v113
	v_cvt_pk_bf16_f32 v4, v4, v4
	ds_write_b16 v46, v4 offset:384
	v_mul_f32_e32 v4, v82, v114
	v_cvt_pk_bf16_f32 v4, v4, v4
	ds_write_b16 v46, v4 offset:640
	v_mul_f32_e32 v4, v83, v115
	v_cvt_pk_bf16_f32 v4, v4, v4
	ds_write_b16 v46, v4 offset:896
	v_mul_f32_e32 v4, v84, v116
	v_cvt_pk_bf16_f32 v4, v4, v4
	ds_write_b16 v46, v4 offset:2176
	v_mul_f32_e32 v4, v85, v117
	v_cvt_pk_bf16_f32 v4, v4, v4
	ds_write_b16 v46, v4 offset:2432
	v_mul_f32_e32 v4, v86, v118
	v_cvt_pk_bf16_f32 v4, v4, v4
	ds_write_b16 v46, v4 offset:2688
	v_mul_f32_e32 v4, v87, v119
	v_cvt_pk_bf16_f32 v4, v4, v4
	ds_write_b16 v46, v4 offset:2944
	v_mul_f32_e32 v4, v88, v120
	v_cvt_pk_bf16_f32 v4, v4, v4
	ds_write_b16 v46, v4 offset:4224
	v_mul_f32_e32 v4, v89, v121
	v_cvt_pk_bf16_f32 v4, v4, v4
	ds_write_b16 v46, v4 offset:4480
	v_mul_f32_e32 v4, v90, v122
	v_cvt_pk_bf16_f32 v4, v4, v4
	ds_write_b16 v46, v4 offset:4736
	v_mul_f32_e32 v4, v91, v123
	v_cvt_pk_bf16_f32 v4, v4, v4
	ds_write_b16 v46, v4 offset:4992
	v_mul_f32_e32 v4, v92, v124
	v_cvt_pk_bf16_f32 v4, v4, v4
	ds_write_b16 v46, v4 offset:6272
	v_mul_f32_e32 v4, v93, v125
	v_cvt_pk_bf16_f32 v4, v4, v4
	ds_write_b16 v46, v4 offset:6528
	v_mul_f32_e32 v4, v94, v126
	v_cvt_pk_bf16_f32 v4, v4, v4
	ds_write_b16 v46, v4 offset:6784
	v_mul_f32_e32 v4, v95, v127
	v_cvt_pk_bf16_f32 v4, v4, v4
	ds_write_b16 v46, v4 offset:7040
	v_mul_f32_e32 v4, v96, v112
	v_cvt_pk_bf16_f32 v4, v4, v4
	ds_write_b16 v46, v4 offset:192
	v_mul_f32_e32 v4, v97, v113
	v_cvt_pk_bf16_f32 v4, v4, v4
	ds_write_b16 v46, v4 offset:448
	v_mul_f32_e32 v4, v98, v114
	v_cvt_pk_bf16_f32 v4, v4, v4
	ds_write_b16 v46, v4 offset:704
	v_mul_f32_e32 v4, v99, v115
	v_cvt_pk_bf16_f32 v4, v4, v4
	ds_write_b16 v46, v4 offset:960
	v_mul_f32_e32 v4, v100, v116
	v_cvt_pk_bf16_f32 v4, v4, v4
	ds_write_b16 v46, v4 offset:2240
	v_mul_f32_e32 v4, v101, v117
	v_cvt_pk_bf16_f32 v4, v4, v4
	ds_write_b16 v46, v4 offset:2496
	v_mul_f32_e32 v4, v102, v118
	v_cvt_pk_bf16_f32 v4, v4, v4
	ds_write_b16 v46, v4 offset:2752
	v_mul_f32_e32 v4, v103, v119
	v_cvt_pk_bf16_f32 v4, v4, v4
	ds_write_b16 v46, v4 offset:3008
	v_mul_f32_e32 v4, v104, v120
	v_cvt_pk_bf16_f32 v4, v4, v4
	ds_write_b16 v46, v4 offset:4288
	v_mul_f32_e32 v4, v105, v121
	v_cvt_pk_bf16_f32 v4, v4, v4
	ds_write_b16 v46, v4 offset:4544
	v_mul_f32_e32 v4, v106, v122
	v_cvt_pk_bf16_f32 v4, v4, v4
	ds_write_b16 v46, v4 offset:4800
	v_mul_f32_e32 v4, v107, v123
	v_cvt_pk_bf16_f32 v4, v4, v4
	ds_write_b16 v46, v4 offset:5056
	v_mul_f32_e32 v4, v108, v124
	v_cvt_pk_bf16_f32 v4, v4, v4
	ds_write_b16 v46, v4 offset:6336
	v_mul_f32_e32 v4, v109, v125
	v_cvt_pk_bf16_f32 v4, v4, v4
	ds_write_b16 v46, v4 offset:6592
	v_mul_f32_e32 v4, v110, v126
	v_cvt_pk_bf16_f32 v4, v4, v4
	ds_write_b16 v46, v4 offset:6848
	v_mul_f32_e32 v4, v111, v127
	v_cvt_pk_bf16_f32 v4, v4, v4
	ds_write_b16 v46, v4 offset:7104
	s_waitcnt lgkmcnt(0)
	ds_read_b128 v[176:179], v219 offset:0
	ds_read_b128 v[180:183], v219 offset:1024
	ds_read_b128 v[184:187], v219 offset:2048
	ds_read_b128 v[188:191], v219 offset:3072
	ds_read_b128 v[192:195], v219 offset:4096
	ds_read_b128 v[196:199], v219 offset:5120
	ds_read_b128 v[200:203], v219 offset:6144
	ds_read_b128 v[204:207], v219 offset:7168
	s_waitcnt lgkmcnt(0)
	v_mov_b32_e32 v253, v252
	global_store_dwordx4 v253, v[176:179], s[86:87]
	v_add_u32_e32 v253, 0x2000, v253
	global_store_dwordx4 v253, v[180:183], s[86:87]
	v_add_u32_e32 v253, 0x2000, v253
	global_store_dwordx4 v253, v[184:187], s[86:87]
	v_add_u32_e32 v253, 0x2000, v253
	global_store_dwordx4 v253, v[188:191], s[86:87]
	v_add_u32_e32 v253, 0x2000, v253
	global_store_dwordx4 v253, v[192:195], s[86:87]
	v_add_u32_e32 v253, 0x2000, v253
	global_store_dwordx4 v253, v[196:199], s[86:87]
	v_add_u32_e32 v253, 0x2000, v253
	global_store_dwordx4 v253, v[200:203], s[86:87]
	v_add_u32_e32 v253, 0x2000, v253
	global_store_dwordx4 v253, v[204:207], s[86:87]
	s_waitcnt vmcnt(0)
	s_barrier
; __device__ __forceinline__ unsigned cvtpk_s(float lo,float hi){f32x2_t v={lo,hi};bf16x2_t b=__builtin_convertvector(v,bf16x2_t);return __builtin_bit_cast(unsigned,b);}
;     ...
;     if(emode>=2){
;       #pragma unroll
;       for(int r=0;r<16;++r){
;         #pragma unroll
;         for(int d0=0;d0<2;++d0){ const float old=__uint_as_float((unsigned)stl[cr0(r)*64+d0*32]<<16); stl[cr0(r)*64+d0*32]=(bf16)(cvtpk_s(old-lam*(o[d0][r]*rli[r]),0.f)&0xffffu);} }
;     } else {
	s_mov_b32 s90, 1
	s_branch .Lfd_pass
.Lfd_epi1:
	v_mov_b32_e32 v253, v252
	global_load_dwordx4 v[176:179], v253, s[86:87]
	v_add_u32_e32 v253, 0x2000, v253
	global_load_dwordx4 v[180:183], v253, s[86:87]
	v_add_u32_e32 v253, 0x2000, v253
	global_load_dwordx4 v[184:187], v253, s[86:87]
	v_add_u32_e32 v253, 0x2000, v253
	global_load_dwordx4 v[188:191], v253, s[86:87]
	v_add_u32_e32 v253, 0x2000, v253
	global_load_dwordx4 v[192:195], v253, s[86:87]
	v_add_u32_e32 v253, 0x2000, v253
	global_load_dwordx4 v[196:199], v253, s[86:87]
	v_add_u32_e32 v253, 0x2000, v253
	global_load_dwordx4 v[200:203], v253, s[86:87]
	v_add_u32_e32 v253, 0x2000, v253
	global_load_dwordx4 v[204:207], v253, s[86:87]
	s_waitcnt vmcnt(0)
	ds_write_b128 v219, v[176:179] offset:0
	ds_write_b128 v219, v[180:183] offset:1024
	ds_write_b128 v219, v[184:187] offset:2048
	ds_write_b128 v219, v[188:191] offset:3072
	ds_write_b128 v219, v[192:195] offset:4096
	ds_write_b128 v219, v[196:199] offset:5120
	ds_write_b128 v219, v[200:203] offset:6144
	ds_write_b128 v219, v[204:207] offset:7168
	s_waitcnt lgkmcnt(0)
	ds_read_u16 v128, v46 offset:0
	ds_read_u16 v129, v46 offset:256
	ds_read_u16 v130, v46 offset:512
	ds_read_u16 v131, v46 offset:768
	ds_read_u16 v132, v46 offset:2048
	ds_read_u16 v133, v46 offset:2304
	ds_read_u16 v134, v46 offset:2560
	ds_read_u16 v135, v46 offset:2816
	ds_read_u16 v136, v46 offset:4096
	ds_read_u16 v137, v46 offset:4352
	ds_read_u16 v138, v46 offset:4608
	ds_read_u16 v139, v46 offset:4864
	ds_read_u16 v140, v46 offset:6144
	ds_read_u16 v141, v46 offset:6400
	ds_read_u16 v142, v46 offset:6656
	ds_read_u16 v143, v46 offset:6912
	s_waitcnt lgkmcnt(0)
	v_mul_f32_e32 v4, v48, v112
	v_lshlrev_b32_e32 v5, 16, v128
	v_fma_f32 v4, -v216, v4, v5
	v_cvt_pk_bf16_f32 v4, v4, v4
	ds_write_b16 v46, v4 offset:0
	v_mul_f32_e32 v4, v49, v113
	v_lshlrev_b32_e32 v5, 16, v129
	v_fma_f32 v4, -v216, v4, v5
	v_cvt_pk_bf16_f32 v4, v4, v4
	ds_write_b16 v46, v4 offset:256
	v_mul_f32_e32 v4, v50, v114
	v_lshlrev_b32_e32 v5, 16, v130
	v_fma_f32 v4, -v216, v4, v5
	v_cvt_pk_bf16_f32 v4, v4, v4
	ds_write_b16 v46, v4 offset:512
	v_mul_f32_e32 v4, v51, v115
	v_lshlrev_b32_e32 v5, 16, v131
	v_fma_f32 v4, -v216, v4, v5
	v_cvt_pk_bf16_f32 v4, v4, v4
	ds_write_b16 v46, v4 offset:768
	v_mul_f32_e32 v4, v52, v116
	v_lshlrev_b32_e32 v5, 16, v132
	v_fma_f32 v4, -v216, v4, v5
	v_cvt_pk_bf16_f32 v4, v4, v4
	ds_write_b16 v46, v4 offset:2048
	v_mul_f32_e32 v4, v53, v117
	v_lshlrev_b32_e32 v5, 16, v133
	v_fma_f32 v4, -v216, v4, v5
	v_cvt_pk_bf16_f32 v4, v4, v4
	ds_write_b16 v46, v4 offset:2304
	v_mul_f32_e32 v4, v54, v118
	v_lshlrev_b32_e32 v5, 16, v134
	v_fma_f32 v4, -v216, v4, v5
	v_cvt_pk_bf16_f32 v4, v4, v4
	ds_write_b16 v46, v4 offset:2560
	v_mul_f32_e32 v4, v55, v119
	v_lshlrev_b32_e32 v5, 16, v135
	v_fma_f32 v4, -v216, v4, v5
	v_cvt_pk_bf16_f32 v4, v4, v4
	ds_write_b16 v46, v4 offset:2816
	v_mul_f32_e32 v4, v56, v120
	v_lshlrev_b32_e32 v5, 16, v136
	v_fma_f32 v4, -v216, v4, v5
	v_cvt_pk_bf16_f32 v4, v4, v4
	ds_write_b16 v46, v4 offset:4096
	v_mul_f32_e32 v4, v57, v121
	v_lshlrev_b32_e32 v5, 16, v137
	v_fma_f32 v4, -v216, v4, v5
	v_cvt_pk_bf16_f32 v4, v4, v4
	ds_write_b16 v46, v4 offset:4352
	v_mul_f32_e32 v4, v58, v122
	v_lshlrev_b32_e32 v5, 16, v138
	v_fma_f32 v4, -v216, v4, v5
	v_cvt_pk_bf16_f32 v4, v4, v4
	ds_write_b16 v46, v4 offset:4608
	v_mul_f32_e32 v4, v59, v123
	v_lshlrev_b32_e32 v5, 16, v139
	v_fma_f32 v4, -v216, v4, v5
	v_cvt_pk_bf16_f32 v4, v4, v4
	ds_write_b16 v46, v4 offset:4864
	v_mul_f32_e32 v4, v60, v124
	v_lshlrev_b32_e32 v5, 16, v140
	v_fma_f32 v4, -v216, v4, v5
	v_cvt_pk_bf16_f32 v4, v4, v4
	ds_write_b16 v46, v4 offset:6144
	v_mul_f32_e32 v4, v61, v125
	v_lshlrev_b32_e32 v5, 16, v141
	v_fma_f32 v4, -v216, v4, v5
	v_cvt_pk_bf16_f32 v4, v4, v4
	ds_write_b16 v46, v4 offset:6400
	v_mul_f32_e32 v4, v62, v126
	v_lshlrev_b32_e32 v5, 16, v142
	v_fma_f32 v4, -v216, v4, v5
	v_cvt_pk_bf16_f32 v4, v4, v4
	ds_write_b16 v46, v4 offset:6656
	v_mul_f32_e32 v4, v63, v127
	v_lshlrev_b32_e32 v5, 16, v143
	v_fma_f32 v4, -v216, v4, v5
	v_cvt_pk_bf16_f32 v4, v4, v4
	ds_write_b16 v46, v4 offset:6912
	ds_read_u16 v128, v46 offset:64
	ds_read_u16 v129, v46 offset:320
	ds_read_u16 v130, v46 offset:576
	ds_read_u16 v131, v46 offset:832
	ds_read_u16 v132, v46 offset:2112
	ds_read_u16 v133, v46 offset:2368
	ds_read_u16 v134, v46 offset:2624
	ds_read_u16 v135, v46 offset:2880
	ds_read_u16 v136, v46 offset:4160
	ds_read_u16 v137, v46 offset:4416
	ds_read_u16 v138, v46 offset:4672
	ds_read_u16 v139, v46 offset:4928
	ds_read_u16 v140, v46 offset:6208
	ds_read_u16 v141, v46 offset:6464
	ds_read_u16 v142, v46 offset:6720
	ds_read_u16 v143, v46 offset:6976
	s_waitcnt lgkmcnt(0)
; __device__ __forceinline__ unsigned cvtpk_s(float lo,float hi){f32x2_t v={lo,hi};bf16x2_t b=__builtin_convertvector(v,bf16x2_t);return __builtin_bit_cast(unsigned,b);}
;     ...
;     if(emode>=2){
;       #pragma unroll
;       for(int r=0;r<16;++r){
;         #pragma unroll
;         for(int d0=0;d0<2;++d0){ const float old=__uint_as_float((unsigned)stl[cr0(r)*64+d0*32]<<16); stl[cr0(r)*64+d0*32]=(bf16)(cvtpk_s(old-lam*(o[d0][r]*rli[r]),0.f)&0xffffu);} }
;     } else {
	v_mul_f32_e32 v4, v64, v112
	v_lshlrev_b32_e32 v5, 16, v128
	v_fma_f32 v4, -v216, v4, v5
	v_cvt_pk_bf16_f32 v4, v4, v4
	ds_write_b16 v46, v4 offset:64
	v_mul_f32_e32 v4, v65, v113
	v_lshlrev_b32_e32 v5, 16, v129
	v_fma_f32 v4, -v216, v4, v5
	v_cvt_pk_bf16_f32 v4, v4, v4
	ds_write_b16 v46, v4 offset:320
	v_mul_f32_e32 v4, v66, v114
	v_lshlrev_b32_e32 v5, 16, v130
	v_fma_f32 v4, -v216, v4, v5
	v_cvt_pk_bf16_f32 v4, v4, v4
	ds_write_b16 v46, v4 offset:576
	v_mul_f32_e32 v4, v67, v115
	v_lshlrev_b32_e32 v5, 16, v131
	v_fma_f32 v4, -v216, v4, v5
	v_cvt_pk_bf16_f32 v4, v4, v4
	ds_write_b16 v46, v4 offset:832
	v_mul_f32_e32 v4, v68, v116
	v_lshlrev_b32_e32 v5, 16, v132
	v_fma_f32 v4, -v216, v4, v5
	v_cvt_pk_bf16_f32 v4, v4, v4
	ds_write_b16 v46, v4 offset:2112
	v_mul_f32_e32 v4, v69, v117
	v_lshlrev_b32_e32 v5, 16, v133
	v_fma_f32 v4, -v216, v4, v5
	v_cvt_pk_bf16_f32 v4, v4, v4
	ds_write_b16 v46, v4 offset:2368
	v_mul_f32_e32 v4, v70, v118
	v_lshlrev_b32_e32 v5, 16, v134
	v_fma_f32 v4, -v216, v4, v5
	v_cvt_pk_bf16_f32 v4, v4, v4
	ds_write_b16 v46, v4 offset:2624
	v_mul_f32_e32 v4, v71, v119
	v_lshlrev_b32_e32 v5, 16, v135
	v_fma_f32 v4, -v216, v4, v5
	v_cvt_pk_bf16_f32 v4, v4, v4
	ds_write_b16 v46, v4 offset:2880
	v_mul_f32_e32 v4, v72, v120
	v_lshlrev_b32_e32 v5, 16, v136
	v_fma_f32 v4, -v216, v4, v5
	v_cvt_pk_bf16_f32 v4, v4, v4
	ds_write_b16 v46, v4 offset:4160
	v_mul_f32_e32 v4, v73, v121
	v_lshlrev_b32_e32 v5, 16, v137
	v_fma_f32 v4, -v216, v4, v5
	v_cvt_pk_bf16_f32 v4, v4, v4
	ds_write_b16 v46, v4 offset:4416
	v_mul_f32_e32 v4, v74, v122
	v_lshlrev_b32_e32 v5, 16, v138
	v_fma_f32 v4, -v216, v4, v5
	v_cvt_pk_bf16_f32 v4, v4, v4
	ds_write_b16 v46, v4 offset:4672
	v_mul_f32_e32 v4, v75, v123
	v_lshlrev_b32_e32 v5, 16, v139
	v_fma_f32 v4, -v216, v4, v5
	v_cvt_pk_bf16_f32 v4, v4, v4
	ds_write_b16 v46, v4 offset:4928
	v_mul_f32_e32 v4, v76, v124
	v_lshlrev_b32_e32 v5, 16, v140
	v_fma_f32 v4, -v216, v4, v5
	v_cvt_pk_bf16_f32 v4, v4, v4
	ds_write_b16 v46, v4 offset:6208
	v_mul_f32_e32 v4, v77, v125
	v_lshlrev_b32_e32 v5, 16, v141
	v_fma_f32 v4, -v216, v4, v5
	v_cvt_pk_bf16_f32 v4, v4, v4
	ds_write_b16 v46, v4 offset:6464
	v_mul_f32_e32 v4, v78, v126
	v_lshlrev_b32_e32 v5, 16, v142
	v_fma_f32 v4, -v216, v4, v5
	v_cvt_pk_bf16_f32 v4, v4, v4
	ds_write_b16 v46, v4 offset:6720
	v_mul_f32_e32 v4, v79, v127
	v_lshlrev_b32_e32 v5, 16, v143
	v_fma_f32 v4, -v216, v4, v5
	v_cvt_pk_bf16_f32 v4, v4, v4
	ds_write_b16 v46, v4 offset:6976
	ds_read_u16 v128, v46 offset:128
	ds_read_u16 v129, v46 offset:384
	ds_read_u16 v130, v46 offset:640
	ds_read_u16 v131, v46 offset:896
	ds_read_u16 v132, v46 offset:2176
	ds_read_u16 v133, v46 offset:2432
	ds_read_u16 v134, v46 offset:2688
	ds_read_u16 v135, v46 offset:2944
	ds_read_u16 v136, v46 offset:4224
	ds_read_u16 v137, v46 offset:4480
	ds_read_u16 v138, v46 offset:4736
	ds_read_u16 v139, v46 offset:4992
	ds_read_u16 v140, v46 offset:6272
	ds_read_u16 v141, v46 offset:6528
	ds_read_u16 v142, v46 offset:6784
	ds_read_u16 v143, v46 offset:7040
	s_waitcnt lgkmcnt(0)
	v_mul_f32_e32 v4, v80, v112
	v_lshlrev_b32_e32 v5, 16, v128
	v_fma_f32 v4, -v216, v4, v5
	v_cvt_pk_bf16_f32 v4, v4, v4
	ds_write_b16 v46, v4 offset:128
	v_mul_f32_e32 v4, v81, v113
	v_lshlrev_b32_e32 v5, 16, v129
	v_fma_f32 v4, -v216, v4, v5
	v_cvt_pk_bf16_f32 v4, v4, v4
	ds_write_b16 v46, v4 offset:384
	v_mul_f32_e32 v4, v82, v114
	v_lshlrev_b32_e32 v5, 16, v130
	v_fma_f32 v4, -v216, v4, v5
	v_cvt_pk_bf16_f32 v4, v4, v4
	ds_write_b16 v46, v4 offset:640
	v_mul_f32_e32 v4, v83, v115
	v_lshlrev_b32_e32 v5, 16, v131
	v_fma_f32 v4, -v216, v4, v5
	v_cvt_pk_bf16_f32 v4, v4, v4
	ds_write_b16 v46, v4 offset:896
	v_mul_f32_e32 v4, v84, v116
	v_lshlrev_b32_e32 v5, 16, v132
	v_fma_f32 v4, -v216, v4, v5
	v_cvt_pk_bf16_f32 v4, v4, v4
	ds_write_b16 v46, v4 offset:2176
	v_mul_f32_e32 v4, v85, v117
	v_lshlrev_b32_e32 v5, 16, v133
	v_fma_f32 v4, -v216, v4, v5
	v_cvt_pk_bf16_f32 v4, v4, v4
	ds_write_b16 v46, v4 offset:2432
	v_mul_f32_e32 v4, v86, v118
	v_lshlrev_b32_e32 v5, 16, v134
	v_fma_f32 v4, -v216, v4, v5
	v_cvt_pk_bf16_f32 v4, v4, v4
	ds_write_b16 v46, v4 offset:2688
	v_mul_f32_e32 v4, v87, v119
	v_lshlrev_b32_e32 v5, 16, v135
	v_fma_f32 v4, -v216, v4, v5
	v_cvt_pk_bf16_f32 v4, v4, v4
	ds_write_b16 v46, v4 offset:2944
	v_mul_f32_e32 v4, v88, v120
	v_lshlrev_b32_e32 v5, 16, v136
	v_fma_f32 v4, -v216, v4, v5
	v_cvt_pk_bf16_f32 v4, v4, v4
	ds_write_b16 v46, v4 offset:4224
	v_mul_f32_e32 v4, v89, v121
	v_lshlrev_b32_e32 v5, 16, v137
	v_fma_f32 v4, -v216, v4, v5
	v_cvt_pk_bf16_f32 v4, v4, v4
	ds_write_b16 v46, v4 offset:4480
	v_mul_f32_e32 v4, v90, v122
	v_lshlrev_b32_e32 v5, 16, v138
	v_fma_f32 v4, -v216, v4, v5
	v_cvt_pk_bf16_f32 v4, v4, v4
	ds_write_b16 v46, v4 offset:4736
	v_mul_f32_e32 v4, v91, v123
	v_lshlrev_b32_e32 v5, 16, v139
	v_fma_f32 v4, -v216, v4, v5
	v_cvt_pk_bf16_f32 v4, v4, v4
	ds_write_b16 v46, v4 offset:4992
	v_mul_f32_e32 v4, v92, v124
	v_lshlrev_b32_e32 v5, 16, v140
	v_fma_f32 v4, -v216, v4, v5
	v_cvt_pk_bf16_f32 v4, v4, v4
	ds_write_b16 v46, v4 offset:6272
	v_mul_f32_e32 v4, v93, v125
	v_lshlrev_b32_e32 v5, 16, v141
	v_fma_f32 v4, -v216, v4, v5
	v_cvt_pk_bf16_f32 v4, v4, v4
	ds_write_b16 v46, v4 offset:6528
	v_mul_f32_e32 v4, v94, v126
	v_lshlrev_b32_e32 v5, 16, v142
	v_fma_f32 v4, -v216, v4, v5
	v_cvt_pk_bf16_f32 v4, v4, v4
	ds_write_b16 v46, v4 offset:6784
	v_mul_f32_e32 v4, v95, v127
	v_lshlrev_b32_e32 v5, 16, v143
	v_fma_f32 v4, -v216, v4, v5
	v_cvt_pk_bf16_f32 v4, v4, v4
	ds_write_b16 v46, v4 offset:7040
	ds_read_u16 v128, v46 offset:192
	ds_read_u16 v129, v46 offset:448
	ds_read_u16 v130, v46 offset:704
	ds_read_u16 v131, v46 offset:960
	ds_read_u16 v132, v46 offset:2240
	ds_read_u16 v133, v46 offset:2496
	ds_read_u16 v134, v46 offset:2752
	ds_read_u16 v135, v46 offset:3008
	ds_read_u16 v136, v46 offset:4288
	ds_read_u16 v137, v46 offset:4544
	ds_read_u16 v138, v46 offset:4800
	ds_read_u16 v139, v46 offset:5056
	ds_read_u16 v140, v46 offset:6336
	ds_read_u16 v141, v46 offset:6592
	ds_read_u16 v142, v46 offset:6848
	ds_read_u16 v143, v46 offset:7104
	s_waitcnt lgkmcnt(0)
; __device__ __forceinline__ unsigned cvtpk_s(float lo,float hi){f32x2_t v={lo,hi};bf16x2_t b=__builtin_convertvector(v,bf16x2_t);return __builtin_bit_cast(unsigned,b);}
; #define ATTN_STORE16(p,v) st16_wt((p),(v))
;     ...
;       for(int r=0;r<16;++r){
;         #pragma unroll
;         for(int d0=0;d0<2;++d0){ const float old=__uint_as_float((unsigned)stl[cr0(r)*64+d0*32]<<16); stl[cr0(r)*64+d0*32]=(bf16)(cvtpk_s(old-lam*(o[d0][r]*rli[r]),0.f)&0xffffu);} }
;     ...
;     } else if(emode==3){
;       #pragma unroll
;       for(int i=0;i<4;++i){const int row=i*8+(lane>>3),ch=lane&7;
;         const u32x4 v0=*(const u32x4*)(stg+row*64+ch*8), v1=*(const u32x4*)(stg+2048+row*64+ch*8);
;         float f[16]; float ss=0.f;
;         #pragma unroll
;         for(int j=0;j<4;++j){ f[2*j]=__uint_as_float(v0[j]<<16); f[2*j+1]=__uint_as_float(v0[j]&0xffff0000u); f[8+2*j]=__uint_as_float(v1[j]<<16); f[8+2*j+1]=__uint_as_float(v1[j]&0xffff0000u); }
;         #pragma unroll
;         for(int j=0;j<16;++j)ss+=f[j]*f[j];
;         ss+=__shfl_xor(ss,1); ss+=__shfl_xor(ss,2); ss+=__shfl_xor(ss,4);
;         const float rn=__builtin_amdgcn_rsqf(ss*(1.f/128.f)+1e-6f)*0.8f;
;         u32x4 w0,w1;
;         #pragma unroll
;         for(int j=0;j<4;++j){ w0[j]=cvtpk_s(f[2*j]*rn,f[2*j+1]*rn); w1[j]=cvtpk_s(f[8+2*j]*rn,f[8+2*j+1]*rn); }
;         ATTN_STORE16(Ow+(long)row*OP+ch*8,w0); ATTN_STORE16(Ow+(long)row*OP+64+ch*8,w1);}
	v_mul_f32_e32 v4, v96, v112
	v_lshlrev_b32_e32 v5, 16, v128
	v_fma_f32 v4, -v216, v4, v5
	v_cvt_pk_bf16_f32 v4, v4, v4
	ds_write_b16 v46, v4 offset:192
	v_mul_f32_e32 v4, v97, v113
	v_lshlrev_b32_e32 v5, 16, v129
	v_fma_f32 v4, -v216, v4, v5
	v_cvt_pk_bf16_f32 v4, v4, v4
	ds_write_b16 v46, v4 offset:448
	v_mul_f32_e32 v4, v98, v114
	v_lshlrev_b32_e32 v5, 16, v130
	v_fma_f32 v4, -v216, v4, v5
	v_cvt_pk_bf16_f32 v4, v4, v4
	ds_write_b16 v46, v4 offset:704
	v_mul_f32_e32 v4, v99, v115
	v_lshlrev_b32_e32 v5, 16, v131
	v_fma_f32 v4, -v216, v4, v5
	v_cvt_pk_bf16_f32 v4, v4, v4
	ds_write_b16 v46, v4 offset:960
	v_mul_f32_e32 v4, v100, v116
	v_lshlrev_b32_e32 v5, 16, v132
	v_fma_f32 v4, -v216, v4, v5
	v_cvt_pk_bf16_f32 v4, v4, v4
	ds_write_b16 v46, v4 offset:2240
	v_mul_f32_e32 v4, v101, v117
	v_lshlrev_b32_e32 v5, 16, v133
	v_fma_f32 v4, -v216, v4, v5
	v_cvt_pk_bf16_f32 v4, v4, v4
	ds_write_b16 v46, v4 offset:2496
	v_mul_f32_e32 v4, v102, v118
	v_lshlrev_b32_e32 v5, 16, v134
	v_fma_f32 v4, -v216, v4, v5
	v_cvt_pk_bf16_f32 v4, v4, v4
	ds_write_b16 v46, v4 offset:2752
	v_mul_f32_e32 v4, v103, v119
	v_lshlrev_b32_e32 v5, 16, v135
	v_fma_f32 v4, -v216, v4, v5
	v_cvt_pk_bf16_f32 v4, v4, v4
	ds_write_b16 v46, v4 offset:3008
	v_mul_f32_e32 v4, v104, v120
	v_lshlrev_b32_e32 v5, 16, v136
	v_fma_f32 v4, -v216, v4, v5
	v_cvt_pk_bf16_f32 v4, v4, v4
	ds_write_b16 v46, v4 offset:4288
	v_mul_f32_e32 v4, v105, v121
	v_lshlrev_b32_e32 v5, 16, v137
	v_fma_f32 v4, -v216, v4, v5
	v_cvt_pk_bf16_f32 v4, v4, v4
	ds_write_b16 v46, v4 offset:4544
	v_mul_f32_e32 v4, v106, v122
	v_lshlrev_b32_e32 v5, 16, v138
	v_fma_f32 v4, -v216, v4, v5
	v_cvt_pk_bf16_f32 v4, v4, v4
	ds_write_b16 v46, v4 offset:4800
	v_mul_f32_e32 v4, v107, v123
	v_lshlrev_b32_e32 v5, 16, v139
	v_fma_f32 v4, -v216, v4, v5
	v_cvt_pk_bf16_f32 v4, v4, v4
	ds_write_b16 v46, v4 offset:5056
	v_mul_f32_e32 v4, v108, v124
	v_lshlrev_b32_e32 v5, 16, v140
	v_fma_f32 v4, -v216, v4, v5
	v_cvt_pk_bf16_f32 v4, v4, v4
	ds_write_b16 v46, v4 offset:6336
	v_mul_f32_e32 v4, v109, v125
	v_lshlrev_b32_e32 v5, 16, v141
	v_fma_f32 v4, -v216, v4, v5
	v_cvt_pk_bf16_f32 v4, v4, v4
	ds_write_b16 v46, v4 offset:6592
	v_mul_f32_e32 v4, v110, v126
	v_lshlrev_b32_e32 v5, 16, v142
	v_fma_f32 v4, -v216, v4, v5
	v_cvt_pk_bf16_f32 v4, v4, v4
	ds_write_b16 v46, v4 offset:6848
	v_mul_f32_e32 v4, v111, v127
	v_lshlrev_b32_e32 v5, 16, v143
	v_fma_f32 v4, -v216, v4, v5
	v_cvt_pk_bf16_f32 v4, v4, v4
	ds_write_b16 v46, v4 offset:7104
	s_waitcnt lgkmcnt(0)
	ds_read_b128 v[176:179], v219 offset:0
	ds_read_b128 v[180:183], v219 offset:1024
	ds_read_b128 v[184:187], v219 offset:2048
	ds_read_b128 v[188:191], v219 offset:3072
	ds_read_b128 v[192:195], v219 offset:4096
	ds_read_b128 v[196:199], v219 offset:5120
	ds_read_b128 v[200:203], v219 offset:6144
	ds_read_b128 v[204:207], v219 offset:7168
	s_waitcnt lgkmcnt(0)
	v_mov_b32_e32 v37, 0x3c000000
	v_mov_b32_e32 v38, 0x358637bd
	v_lshlrev_b32_e32 v112, 16, v176
	v_and_b32_e32 v113, 0xffff0000, v176
	v_lshlrev_b32_e32 v114, 16, v177
	v_and_b32_e32 v115, 0xffff0000, v177
	v_lshlrev_b32_e32 v116, 16, v178
	v_and_b32_e32 v117, 0xffff0000, v178
	v_lshlrev_b32_e32 v118, 16, v179
	v_and_b32_e32 v119, 0xffff0000, v179
	v_mul_f32_e32 v4, v112, v112
	v_fmac_f32_e32 v4, v113, v113
	v_fmac_f32_e32 v4, v114, v114
	v_fmac_f32_e32 v4, v115, v115
	v_fmac_f32_e32 v4, v116, v116
	v_fmac_f32_e32 v4, v117, v117
	v_fmac_f32_e32 v4, v118, v118
	v_fmac_f32_e32 v4, v119, v119
	s_nop 1
	v_mov_b32_dpp v5, v4 row_ror:8 row_mask:0xf bank_mask:0xf
	v_add_f32_e32 v4, v4, v5
	s_nop 1
	v_mov_b32_dpp v5, v4 row_ror:4 row_mask:0xf bank_mask:0xf
	v_add_f32_e32 v4, v4, v5
	s_nop 1
	v_mov_b32_dpp v5, v4 row_ror:2 row_mask:0xf bank_mask:0xf
	v_add_f32_e32 v4, v4, v5
	s_nop 1
	v_mov_b32_dpp v5, v4 row_ror:1 row_mask:0xf bank_mask:0xf
	v_add_f32_e32 v4, v4, v5
	v_fma_f32 v4, v4, v37, v38
	v_rsq_f32_e32 v4, v4
	s_nop 0
	v_mul_f32_e32 v4, 0x3f4ccccd, v4
	v_mul_f32_e32 v112, v112, v4
	v_mul_f32_e32 v113, v113, v4
	v_mul_f32_e32 v114, v114, v4
	v_mul_f32_e32 v115, v115, v4
	v_mul_f32_e32 v116, v116, v4
	v_mul_f32_e32 v117, v117, v4
	v_mul_f32_e32 v118, v118, v4
	v_mul_f32_e32 v119, v119, v4
	v_cvt_pk_bf16_f32 v176, v112, v113
	v_cvt_pk_bf16_f32 v177, v114, v115
	v_cvt_pk_bf16_f32 v178, v116, v117
	v_cvt_pk_bf16_f32 v179, v118, v119
	v_mov_b32_e32 v253, v252
	global_store_dwordx4 v253, v[176:179], s[86:87]
	v_lshlrev_b32_e32 v112, 16, v180
	v_and_b32_e32 v113, 0xffff0000, v180
	v_lshlrev_b32_e32 v114, 16, v181
	v_and_b32_e32 v115, 0xffff0000, v181
	v_lshlrev_b32_e32 v116, 16, v182
	v_and_b32_e32 v117, 0xffff0000, v182
	v_lshlrev_b32_e32 v118, 16, v183
	v_and_b32_e32 v119, 0xffff0000, v183
	v_mul_f32_e32 v4, v112, v112
	v_fmac_f32_e32 v4, v113, v113
	v_fmac_f32_e32 v4, v114, v114
	v_fmac_f32_e32 v4, v115, v115
	v_fmac_f32_e32 v4, v116, v116
	v_fmac_f32_e32 v4, v117, v117
	v_fmac_f32_e32 v4, v118, v118
	v_fmac_f32_e32 v4, v119, v119
	s_nop 1
	v_mov_b32_dpp v5, v4 row_ror:8 row_mask:0xf bank_mask:0xf
	v_add_f32_e32 v4, v4, v5
	s_nop 1
	v_mov_b32_dpp v5, v4 row_ror:4 row_mask:0xf bank_mask:0xf
	v_add_f32_e32 v4, v4, v5
	s_nop 1
	v_mov_b32_dpp v5, v4 row_ror:2 row_mask:0xf bank_mask:0xf
	v_add_f32_e32 v4, v4, v5
	s_nop 1
	v_mov_b32_dpp v5, v4 row_ror:1 row_mask:0xf bank_mask:0xf
	v_add_f32_e32 v4, v4, v5
	v_fma_f32 v4, v4, v37, v38
	v_rsq_f32_e32 v4, v4
	s_nop 0
	v_mul_f32_e32 v4, 0x3f4ccccd, v4
	v_mul_f32_e32 v112, v112, v4
	v_mul_f32_e32 v113, v113, v4
	v_mul_f32_e32 v114, v114, v4
	v_mul_f32_e32 v115, v115, v4
	v_mul_f32_e32 v116, v116, v4
	v_mul_f32_e32 v117, v117, v4
	v_mul_f32_e32 v118, v118, v4
	v_mul_f32_e32 v119, v119, v4
; __device__ __forceinline__ unsigned cvtpk_s(float lo,float hi){f32x2_t v={lo,hi};bf16x2_t b=__builtin_convertvector(v,bf16x2_t);return __builtin_bit_cast(unsigned,b);}
; #define ATTN_STORE16(p,v) st16_wt((p),(v))
;     ...
;     } else if(emode==3){
;       #pragma unroll
;       for(int i=0;i<4;++i){const int row=i*8+(lane>>3),ch=lane&7;
;         const u32x4 v0=*(const u32x4*)(stg+row*64+ch*8), v1=*(const u32x4*)(stg+2048+row*64+ch*8);
;         float f[16]; float ss=0.f;
;         #pragma unroll
;         for(int j=0;j<4;++j){ f[2*j]=__uint_as_float(v0[j]<<16); f[2*j+1]=__uint_as_float(v0[j]&0xffff0000u); f[8+2*j]=__uint_as_float(v1[j]<<16); f[8+2*j+1]=__uint_as_float(v1[j]&0xffff0000u); }
;         #pragma unroll
;         for(int j=0;j<16;++j)ss+=f[j]*f[j];
;         ss+=__shfl_xor(ss,1); ss+=__shfl_xor(ss,2); ss+=__shfl_xor(ss,4);
;         const float rn=__builtin_amdgcn_rsqf(ss*(1.f/128.f)+1e-6f)*0.8f;
;         u32x4 w0,w1;
;         #pragma unroll
;         for(int j=0;j<4;++j){ w0[j]=cvtpk_s(f[2*j]*rn,f[2*j+1]*rn); w1[j]=cvtpk_s(f[8+2*j]*rn,f[8+2*j+1]*rn); }
;         ATTN_STORE16(Ow+(long)row*OP+ch*8,w0); ATTN_STORE16(Ow+(long)row*OP+64+ch*8,w1);}
	v_cvt_pk_bf16_f32 v180, v112, v113
	v_cvt_pk_bf16_f32 v181, v114, v115
	v_cvt_pk_bf16_f32 v182, v116, v117
	v_cvt_pk_bf16_f32 v183, v118, v119
	v_add_u32_e32 v253, 0x2000, v253
	global_store_dwordx4 v253, v[180:183], s[86:87]
	v_lshlrev_b32_e32 v112, 16, v184
	v_and_b32_e32 v113, 0xffff0000, v184
	v_lshlrev_b32_e32 v114, 16, v185
	v_and_b32_e32 v115, 0xffff0000, v185
	v_lshlrev_b32_e32 v116, 16, v186
	v_and_b32_e32 v117, 0xffff0000, v186
	v_lshlrev_b32_e32 v118, 16, v187
	v_and_b32_e32 v119, 0xffff0000, v187
	v_mul_f32_e32 v4, v112, v112
	v_fmac_f32_e32 v4, v113, v113
	v_fmac_f32_e32 v4, v114, v114
	v_fmac_f32_e32 v4, v115, v115
	v_fmac_f32_e32 v4, v116, v116
	v_fmac_f32_e32 v4, v117, v117
	v_fmac_f32_e32 v4, v118, v118
	v_fmac_f32_e32 v4, v119, v119
	s_nop 1
	v_mov_b32_dpp v5, v4 row_ror:8 row_mask:0xf bank_mask:0xf
	v_add_f32_e32 v4, v4, v5
	s_nop 1
	v_mov_b32_dpp v5, v4 row_ror:4 row_mask:0xf bank_mask:0xf
	v_add_f32_e32 v4, v4, v5
	s_nop 1
	v_mov_b32_dpp v5, v4 row_ror:2 row_mask:0xf bank_mask:0xf
	v_add_f32_e32 v4, v4, v5
	s_nop 1
	v_mov_b32_dpp v5, v4 row_ror:1 row_mask:0xf bank_mask:0xf
	v_add_f32_e32 v4, v4, v5
	v_fma_f32 v4, v4, v37, v38
	v_rsq_f32_e32 v4, v4
	s_nop 0
	v_mul_f32_e32 v4, 0x3f4ccccd, v4
	v_mul_f32_e32 v112, v112, v4
	v_mul_f32_e32 v113, v113, v4
	v_mul_f32_e32 v114, v114, v4
	v_mul_f32_e32 v115, v115, v4
	v_mul_f32_e32 v116, v116, v4
	v_mul_f32_e32 v117, v117, v4
	v_mul_f32_e32 v118, v118, v4
	v_mul_f32_e32 v119, v119, v4
	v_cvt_pk_bf16_f32 v184, v112, v113
	v_cvt_pk_bf16_f32 v185, v114, v115
	v_cvt_pk_bf16_f32 v186, v116, v117
	v_cvt_pk_bf16_f32 v187, v118, v119
	v_add_u32_e32 v253, 0x2000, v253
	global_store_dwordx4 v253, v[184:187], s[86:87]
	v_lshlrev_b32_e32 v112, 16, v188
	v_and_b32_e32 v113, 0xffff0000, v188
	v_lshlrev_b32_e32 v114, 16, v189
	v_and_b32_e32 v115, 0xffff0000, v189
	v_lshlrev_b32_e32 v116, 16, v190
	v_and_b32_e32 v117, 0xffff0000, v190
	v_lshlrev_b32_e32 v118, 16, v191
	v_and_b32_e32 v119, 0xffff0000, v191
	v_mul_f32_e32 v4, v112, v112
	v_fmac_f32_e32 v4, v113, v113
	v_fmac_f32_e32 v4, v114, v114
	v_fmac_f32_e32 v4, v115, v115
	v_fmac_f32_e32 v4, v116, v116
	v_fmac_f32_e32 v4, v117, v117
	v_fmac_f32_e32 v4, v118, v118
	v_fmac_f32_e32 v4, v119, v119
	s_nop 1
	v_mov_b32_dpp v5, v4 row_ror:8 row_mask:0xf bank_mask:0xf
	v_add_f32_e32 v4, v4, v5
	s_nop 1
	v_mov_b32_dpp v5, v4 row_ror:4 row_mask:0xf bank_mask:0xf
	v_add_f32_e32 v4, v4, v5
	s_nop 1
	v_mov_b32_dpp v5, v4 row_ror:2 row_mask:0xf bank_mask:0xf
	v_add_f32_e32 v4, v4, v5
	s_nop 1
	v_mov_b32_dpp v5, v4 row_ror:1 row_mask:0xf bank_mask:0xf
	v_add_f32_e32 v4, v4, v5
	v_fma_f32 v4, v4, v37, v38
	v_rsq_f32_e32 v4, v4
	s_nop 0
	v_mul_f32_e32 v4, 0x3f4ccccd, v4
	v_mul_f32_e32 v112, v112, v4
	v_mul_f32_e32 v113, v113, v4
	v_mul_f32_e32 v114, v114, v4
	v_mul_f32_e32 v115, v115, v4
	v_mul_f32_e32 v116, v116, v4
	v_mul_f32_e32 v117, v117, v4
	v_mul_f32_e32 v118, v118, v4
	v_mul_f32_e32 v119, v119, v4
	v_cvt_pk_bf16_f32 v188, v112, v113
	v_cvt_pk_bf16_f32 v189, v114, v115
	v_cvt_pk_bf16_f32 v190, v116, v117
	v_cvt_pk_bf16_f32 v191, v118, v119
	v_add_u32_e32 v253, 0x2000, v253
	global_store_dwordx4 v253, v[188:191], s[86:87]
	v_lshlrev_b32_e32 v112, 16, v192
	v_and_b32_e32 v113, 0xffff0000, v192
	v_lshlrev_b32_e32 v114, 16, v193
	v_and_b32_e32 v115, 0xffff0000, v193
	v_lshlrev_b32_e32 v116, 16, v194
	v_and_b32_e32 v117, 0xffff0000, v194
	v_lshlrev_b32_e32 v118, 16, v195
	v_and_b32_e32 v119, 0xffff0000, v195
	v_mul_f32_e32 v4, v112, v112
	v_fmac_f32_e32 v4, v113, v113
	v_fmac_f32_e32 v4, v114, v114
	v_fmac_f32_e32 v4, v115, v115
	v_fmac_f32_e32 v4, v116, v116
	v_fmac_f32_e32 v4, v117, v117
	v_fmac_f32_e32 v4, v118, v118
	v_fmac_f32_e32 v4, v119, v119
	s_nop 1
	v_mov_b32_dpp v5, v4 row_ror:8 row_mask:0xf bank_mask:0xf
	v_add_f32_e32 v4, v4, v5
	s_nop 1
	v_mov_b32_dpp v5, v4 row_ror:4 row_mask:0xf bank_mask:0xf
	v_add_f32_e32 v4, v4, v5
	s_nop 1
	v_mov_b32_dpp v5, v4 row_ror:2 row_mask:0xf bank_mask:0xf
	v_add_f32_e32 v4, v4, v5
	s_nop 1
	v_mov_b32_dpp v5, v4 row_ror:1 row_mask:0xf bank_mask:0xf
	v_add_f32_e32 v4, v4, v5
	v_fma_f32 v4, v4, v37, v38
	v_rsq_f32_e32 v4, v4
	s_nop 0
	v_mul_f32_e32 v4, 0x3f4ccccd, v4
	v_mul_f32_e32 v112, v112, v4
	v_mul_f32_e32 v113, v113, v4
	v_mul_f32_e32 v114, v114, v4
	v_mul_f32_e32 v115, v115, v4
	v_mul_f32_e32 v116, v116, v4
	v_mul_f32_e32 v117, v117, v4
	v_mul_f32_e32 v118, v118, v4
	v_mul_f32_e32 v119, v119, v4
	v_cvt_pk_bf16_f32 v192, v112, v113
	v_cvt_pk_bf16_f32 v193, v114, v115
	v_cvt_pk_bf16_f32 v194, v116, v117
	v_cvt_pk_bf16_f32 v195, v118, v119
; __device__ __forceinline__ unsigned cvtpk_s(float lo,float hi){f32x2_t v={lo,hi};bf16x2_t b=__builtin_convertvector(v,bf16x2_t);return __builtin_bit_cast(unsigned,b);}
; #define ATTN_STORE16(p,v) st16_wt((p),(v))
;     ...
;     } else if(emode==3){
;       #pragma unroll
;       for(int i=0;i<4;++i){const int row=i*8+(lane>>3),ch=lane&7;
;         const u32x4 v0=*(const u32x4*)(stg+row*64+ch*8), v1=*(const u32x4*)(stg+2048+row*64+ch*8);
;         float f[16]; float ss=0.f;
;         #pragma unroll
;         for(int j=0;j<4;++j){ f[2*j]=__uint_as_float(v0[j]<<16); f[2*j+1]=__uint_as_float(v0[j]&0xffff0000u); f[8+2*j]=__uint_as_float(v1[j]<<16); f[8+2*j+1]=__uint_as_float(v1[j]&0xffff0000u); }
;         #pragma unroll
;         for(int j=0;j<16;++j)ss+=f[j]*f[j];
;         ss+=__shfl_xor(ss,1); ss+=__shfl_xor(ss,2); ss+=__shfl_xor(ss,4);
;         const float rn=__builtin_amdgcn_rsqf(ss*(1.f/128.f)+1e-6f)*0.8f;
;         u32x4 w0,w1;
;         #pragma unroll
;         for(int j=0;j<4;++j){ w0[j]=cvtpk_s(f[2*j]*rn,f[2*j+1]*rn); w1[j]=cvtpk_s(f[8+2*j]*rn,f[8+2*j+1]*rn); }
;         ATTN_STORE16(Ow+(long)row*OP+ch*8,w0); ATTN_STORE16(Ow+(long)row*OP+64+ch*8,w1);}
	v_add_u32_e32 v253, 0x2000, v253
	global_store_dwordx4 v253, v[192:195], s[86:87]
	v_lshlrev_b32_e32 v112, 16, v196
	v_and_b32_e32 v113, 0xffff0000, v196
	v_lshlrev_b32_e32 v114, 16, v197
	v_and_b32_e32 v115, 0xffff0000, v197
	v_lshlrev_b32_e32 v116, 16, v198
	v_and_b32_e32 v117, 0xffff0000, v198
	v_lshlrev_b32_e32 v118, 16, v199
	v_and_b32_e32 v119, 0xffff0000, v199
	v_mul_f32_e32 v4, v112, v112
	v_fmac_f32_e32 v4, v113, v113
	v_fmac_f32_e32 v4, v114, v114
	v_fmac_f32_e32 v4, v115, v115
	v_fmac_f32_e32 v4, v116, v116
	v_fmac_f32_e32 v4, v117, v117
	v_fmac_f32_e32 v4, v118, v118
	v_fmac_f32_e32 v4, v119, v119
	s_nop 1
	v_mov_b32_dpp v5, v4 row_ror:8 row_mask:0xf bank_mask:0xf
	v_add_f32_e32 v4, v4, v5
	s_nop 1
	v_mov_b32_dpp v5, v4 row_ror:4 row_mask:0xf bank_mask:0xf
	v_add_f32_e32 v4, v4, v5
	s_nop 1
	v_mov_b32_dpp v5, v4 row_ror:2 row_mask:0xf bank_mask:0xf
	v_add_f32_e32 v4, v4, v5
	s_nop 1
	v_mov_b32_dpp v5, v4 row_ror:1 row_mask:0xf bank_mask:0xf
	v_add_f32_e32 v4, v4, v5
	v_fma_f32 v4, v4, v37, v38
	v_rsq_f32_e32 v4, v4
	s_nop 0
	v_mul_f32_e32 v4, 0x3f4ccccd, v4
	v_mul_f32_e32 v112, v112, v4
	v_mul_f32_e32 v113, v113, v4
	v_mul_f32_e32 v114, v114, v4
	v_mul_f32_e32 v115, v115, v4
	v_mul_f32_e32 v116, v116, v4
	v_mul_f32_e32 v117, v117, v4
	v_mul_f32_e32 v118, v118, v4
	v_mul_f32_e32 v119, v119, v4
	v_cvt_pk_bf16_f32 v196, v112, v113
	v_cvt_pk_bf16_f32 v197, v114, v115
	v_cvt_pk_bf16_f32 v198, v116, v117
	v_cvt_pk_bf16_f32 v199, v118, v119
	v_add_u32_e32 v253, 0x2000, v253
	global_store_dwordx4 v253, v[196:199], s[86:87]
	v_lshlrev_b32_e32 v112, 16, v200
	v_and_b32_e32 v113, 0xffff0000, v200
	v_lshlrev_b32_e32 v114, 16, v201
	v_and_b32_e32 v115, 0xffff0000, v201
	v_lshlrev_b32_e32 v116, 16, v202
	v_and_b32_e32 v117, 0xffff0000, v202
	v_lshlrev_b32_e32 v118, 16, v203
	v_and_b32_e32 v119, 0xffff0000, v203
	v_mul_f32_e32 v4, v112, v112
	v_fmac_f32_e32 v4, v113, v113
	v_fmac_f32_e32 v4, v114, v114
	v_fmac_f32_e32 v4, v115, v115
	v_fmac_f32_e32 v4, v116, v116
	v_fmac_f32_e32 v4, v117, v117
	v_fmac_f32_e32 v4, v118, v118
	v_fmac_f32_e32 v4, v119, v119
	s_nop 1
	v_mov_b32_dpp v5, v4 row_ror:8 row_mask:0xf bank_mask:0xf
	v_add_f32_e32 v4, v4, v5
	s_nop 1
	v_mov_b32_dpp v5, v4 row_ror:4 row_mask:0xf bank_mask:0xf
	v_add_f32_e32 v4, v4, v5
	s_nop 1
	v_mov_b32_dpp v5, v4 row_ror:2 row_mask:0xf bank_mask:0xf
	v_add_f32_e32 v4, v4, v5
	s_nop 1
	v_mov_b32_dpp v5, v4 row_ror:1 row_mask:0xf bank_mask:0xf
	v_add_f32_e32 v4, v4, v5
	v_fma_f32 v4, v4, v37, v38
	v_rsq_f32_e32 v4, v4
	s_nop 0
	v_mul_f32_e32 v4, 0x3f4ccccd, v4
	v_mul_f32_e32 v112, v112, v4
	v_mul_f32_e32 v113, v113, v4
	v_mul_f32_e32 v114, v114, v4
	v_mul_f32_e32 v115, v115, v4
	v_mul_f32_e32 v116, v116, v4
	v_mul_f32_e32 v117, v117, v4
	v_mul_f32_e32 v118, v118, v4
	v_mul_f32_e32 v119, v119, v4
	v_cvt_pk_bf16_f32 v200, v112, v113
	v_cvt_pk_bf16_f32 v201, v114, v115
	v_cvt_pk_bf16_f32 v202, v116, v117
	v_cvt_pk_bf16_f32 v203, v118, v119
	v_add_u32_e32 v253, 0x2000, v253
	global_store_dwordx4 v253, v[200:203], s[86:87]
	v_lshlrev_b32_e32 v112, 16, v204
	v_and_b32_e32 v113, 0xffff0000, v204
	v_lshlrev_b32_e32 v114, 16, v205
	v_and_b32_e32 v115, 0xffff0000, v205
	v_lshlrev_b32_e32 v116, 16, v206
	v_and_b32_e32 v117, 0xffff0000, v206
	v_lshlrev_b32_e32 v118, 16, v207
	v_and_b32_e32 v119, 0xffff0000, v207
	v_mul_f32_e32 v4, v112, v112
	v_fmac_f32_e32 v4, v113, v113
	v_fmac_f32_e32 v4, v114, v114
	v_fmac_f32_e32 v4, v115, v115
	v_fmac_f32_e32 v4, v116, v116
	v_fmac_f32_e32 v4, v117, v117
	v_fmac_f32_e32 v4, v118, v118
	v_fmac_f32_e32 v4, v119, v119
	s_nop 1
	v_mov_b32_dpp v5, v4 row_ror:8 row_mask:0xf bank_mask:0xf
	v_add_f32_e32 v4, v4, v5
	s_nop 1
	v_mov_b32_dpp v5, v4 row_ror:4 row_mask:0xf bank_mask:0xf
	v_add_f32_e32 v4, v4, v5
	s_nop 1
	v_mov_b32_dpp v5, v4 row_ror:2 row_mask:0xf bank_mask:0xf
	v_add_f32_e32 v4, v4, v5
	s_nop 1
	v_mov_b32_dpp v5, v4 row_ror:1 row_mask:0xf bank_mask:0xf
	v_add_f32_e32 v4, v4, v5
	v_fma_f32 v4, v4, v37, v38
	v_rsq_f32_e32 v4, v4
	s_nop 0
	v_mul_f32_e32 v4, 0x3f4ccccd, v4
	v_mul_f32_e32 v112, v112, v4
	v_mul_f32_e32 v113, v113, v4
	v_mul_f32_e32 v114, v114, v4
	v_mul_f32_e32 v115, v115, v4
	v_mul_f32_e32 v116, v116, v4
	v_mul_f32_e32 v117, v117, v4
	v_mul_f32_e32 v118, v118, v4
	v_mul_f32_e32 v119, v119, v4
	v_cvt_pk_bf16_f32 v204, v112, v113
	v_cvt_pk_bf16_f32 v205, v114, v115
	v_cvt_pk_bf16_f32 v206, v116, v117
	v_cvt_pk_bf16_f32 v207, v118, v119
	v_add_u32_e32 v253, 0x2000, v253
	global_store_dwordx4 v253, v[204:207], s[86:87]
	s_waitcnt vmcnt(0) lgkmcnt(0)
	s_barrier
	s_branch .LBB0_1511

; __global__ void __launch_bounds__(NWAVES * 64, 2) mk(Args args) {
	.amdhsa_kernel _Z2mk4Args
		.amdhsa_group_segment_fixed_size 0
		.amdhsa_private_segment_fixed_size 0
		.amdhsa_kernarg_size 624
		.amdhsa_user_sgpr_count 2
		.amdhsa_user_sgpr_dispatch_ptr 0
		.amdhsa_user_sgpr_queue_ptr 0
		.amdhsa_user_sgpr_kernarg_segment_ptr 1
		.amdhsa_user_sgpr_dispatch_id 0
		.amdhsa_user_sgpr_kernarg_preload_length 0
		.amdhsa_user_sgpr_kernarg_preload_offset 0
		.amdhsa_user_sgpr_private_segment_size 0
		.amdhsa_uses_dynamic_stack 0
		.amdhsa_enable_private_segment 0
		.amdhsa_system_sgpr_workgroup_id_x 1
		.amdhsa_system_sgpr_workgroup_id_y 0
		.amdhsa_system_sgpr_workgroup_id_z 0
		.amdhsa_system_sgpr_workgroup_info 0
		.amdhsa_system_vgpr_workitem_id 0
		.amdhsa_next_free_vgpr 256
		.amdhsa_next_free_sgpr 98
		.amdhsa_accum_offset 256
		.amdhsa_reserve_vcc 1
		.amdhsa_float_round_mode_32 0
		.amdhsa_float_round_mode_16_64 0
		.amdhsa_float_denorm_mode_32 3
		.amdhsa_float_denorm_mode_16_64 3
		.amdhsa_dx10_clamp 1
		.amdhsa_ieee_mode 1
		.amdhsa_fp16_overflow 0
		.amdhsa_tg_split 0
		.amdhsa_exception_fp_ieee_invalid_op 0
		.amdhsa_exception_fp_denorm_src 0
		.amdhsa_exception_fp_ieee_div_zero 0
		.amdhsa_exception_fp_ieee_overflow 0
		.amdhsa_exception_fp_ieee_underflow 0
		.amdhsa_exception_fp_ieee_inexact 0
		.amdhsa_exception_int_div_zero 0
	.end_amdhsa_kernel

; __global__ void __launch_bounds__(NWAVES * 64, 2) mk(Args args) {
amdhsa.kernels:
  - .agpr_count:     0
    .args:
      - .offset:         0
        .size:           368
        .value_kind:     by_value
      - .offset:         368
        .size:           4
        .value_kind:     hidden_block_count_x
      - .offset:         372
        .size:           4
        .value_kind:     hidden_block_count_y
      - .offset:         376
        .size:           4
        .value_kind:     hidden_block_count_z
      - .offset:         380
        .size:           2
        .value_kind:     hidden_group_size_x
      - .offset:         382
        .size:           2
        .value_kind:     hidden_group_size_y
      - .offset:         384
        .size:           2
        .value_kind:     hidden_group_size_z
      - .offset:         386
        .size:           2
        .value_kind:     hidden_remainder_x
      - .offset:         388
        .size:           2
        .value_kind:     hidden_remainder_y
      - .offset:         390
        .size:           2
        .value_kind:     hidden_remainder_z
      - .offset:         408
        .size:           8
        .value_kind:     hidden_global_offset_x
      - .offset:         416
        .size:           8
        .value_kind:     hidden_global_offset_y
      - .offset:         424
        .size:           8
        .value_kind:     hidden_global_offset_z
      - .offset:         432
        .size:           2
        .value_kind:     hidden_grid_dims
      - .offset:         488
        .size:           4
        .value_kind:     hidden_dynamic_lds_size
    .group_segment_fixed_size: 0
    .kernarg_segment_align: 8
    .kernarg_segment_size: 624
    .language:       OpenCL C
    .language_version:
      - 2
      - 0
    .max_flat_workgroup_size: 512
    .name:           _Z2mk4Args
    .private_segment_fixed_size: 0
    .sgpr_count:     104
    .sgpr_spill_count: 81
    .symbol:         _Z2mk4Args.kd
    .uniform_work_group_size: 1
    .uses_dynamic_stack: false
    .vgpr_count:     256
    .vgpr_spill_count: 0
    .wavefront_size: 64
